# speedup vs baseline: 1.0187x; 1.0187x over previous
; template <int DQK, int MODE> ...
;     ...
;   auto lstore = [&](const TRegs& R, int st) {
;     u16* Ks = lds + st * STG;
;     u16* Vs = Ks + KT;
; #pragma unroll
;     for (int i = 0; i < NKL; ++i) {
;       int c = tid + i * 256;
;       int row = c / KCH, cc = c % KCH;
;       *(u32x4*)(Ks + row * KST + cc * 8) = R.k[i];
;     }
; #pragma unroll
;     for (int i = 0; i < 2; ++i) {
;       int c = tid + i * 256;
;       int d = c >> 3, cc = c & 7;
;       u32x2 lo = {R.v[i].x, R.v[i].y}, hi = {R.v[i].z, R.v[i].w};
;       *(u32x2*)(Vs + d * VST + cc * 8) = lo;
;       *(u32x2*)(Vs + d * VST + cc * 8 + 4) = hi;
;     }
;   };
;   f32x16 O[2];
; #pragma unroll
;   for (int du = 0; du < 2; ++du)
; #pragma unroll
;     for (int r = 0; r < 16; ++r) O[du][r] = 0.f;
;   float m_run = 0.f, lsum = 0.f;
;   bool first = true;
;   float carry = active ? 1.f : 0.f;
;   const int dir = (MODE == 2) ? -1 : 1;
;   const int jstart = (MODE == 2) ? jhi : jlo;
;   const int ntile = jhi - jlo + 1;
;   auto step = [&](TRegs& R, int it) -> bool {
;     const int j = jstart + dir * it;
;     const int st = it & 1;
;     lstore(R, st);
;     if (MODE == 2) {
;       int alive = (carry != 0.f) ? 1 : 0;
;       if (!__syncthreads_or(alive)) return false;
;     } else {
;       __syncthreads();
;     }
;     if (it + 2 < ntile) gload(R, j + 2 * dir);
.LBB0_985:
	v_lshlrev_b32_e32 v176, 3, v15
	v_mov_b32_e32 v49, 0
	s_cmp_lt_i32 s4, 0xfff00000
	v_mov_b32_e32 v48, 0
	v_mov_b32_e32 v47, 0
	v_mov_b32_e32 v46, 0
	v_mov_b32_e32 v45, 0
	v_mov_b32_e32 v44, 0
	v_mov_b32_e32 v43, 0
	v_mov_b32_e32 v42, 0
	v_mov_b32_e32 v41, 0
	v_mov_b32_e32 v40, 0
	v_mov_b32_e32 v39, 0
	v_mov_b32_e32 v38, 0
	v_mov_b32_e32 v37, 0
	v_mov_b32_e32 v36, 0
	v_mov_b32_e32 v35, 0
	v_mov_b32_e32 v34, 0
	v_mov_b32_e32 v33, 0
	v_mov_b32_e32 v32, 0
	v_mov_b32_e32 v31, 0
	v_mov_b32_e32 v30, 0
	v_mov_b32_e32 v29, 0
	v_mov_b32_e32 v28, 0
	v_mov_b32_e32 v27, 0
	v_mov_b32_e32 v26, 0
	v_mov_b32_e32 v25, 0
	v_mov_b32_e32 v24, 0
	v_mov_b32_e32 v23, 0
	v_mov_b32_e32 v22, 0
	v_mov_b32_e32 v21, 0
	v_mov_b32_e32 v20, 0
	v_mov_b32_e32 v19, 0
	v_mov_b32_e32 v18, 0
	v_mov_b32_e32 v177, 0
	s_cbranch_scc1 .LBB0_1002
	v_lshl_add_u64 v[178:179], v[4:5], 1, s[16:17]
	v_ashrrev_i32_e32 v5, 7, v14
	v_cndmask_b32_e64 v5, 0, v5, s[0:1]
	v_add_u32_e32 v199, s3, v5
	v_max_i32_e32 v5, 0x100000, v199
	s_movk_i32 s0, 0xd0
	v_add_u32_e32 v200, 0xfff00000, v5
	v_mul_lo_u32 v5, v171, s0
	v_lshl_add_u32 v201, v4, 1, v5
	v_mul_lo_u32 v4, v173, s0
	v_lshl_add_u32 v202, v6, 1, v4
	v_mul_lo_u32 v4, v175, s0
	v_lshl_add_u32 v203, v10, 1, v4
	v_lshrrev_b32_e32 v4, 3, v14
	s_movk_i32 s4, 0x98
	v_mad_u64_u32 v[184:185], s[0:1], v4, s4, v[2:3]
	v_lshrrev_b32_e32 v4, 3, v16
	v_mad_u64_u32 v[186:187], s[0:1], v4, s4, v[2:3]
	v_lshlrev_b32_e32 v2, 1, v176
	v_mul_u32_u24_e32 v4, 0x68, v172
	v_lshl_add_u32 v185, v4, 1, v2
	v_sub_u32_e32 v2, v2, v176
	v_mul_u32_u24_e32 v4, 0x4c, v172
	s_mov_b32 s13, s37
	v_lshl_add_u32 v187, v4, 1, v2
	s_lshl_b64 s[0:1], s[12:13], 13
	v_and_b32_e32 v2, 7, v14
	v_lshl_or_b32 v4, v2, 4, s0
	v_mov_b32_e32 v5, s1
	v_lshl_add_u64 v[180:181], v[6:7], 1, s[16:17]
	v_lshl_add_u64 v[6:7], v[8:9], 1, v[4:5]
	v_lshl_add_u64 v[4:5], v[12:13], 1, v[4:5]
	v_mov_b32_e32 v16, v3
	v_mov_b32_e32 v17, v3
	v_lshl_add_u64 v[182:183], v[10:11], 1, s[16:17]
	v_lshl_add_u64 v[188:189], s[14:15], 0, v[6:7]
	v_lshl_add_u64 v[190:191], s[14:15], 0, v[4:5]
	v_mov_b32_e32 v2, v3
	v_mov_b32_e32 v4, v3
	v_mov_b32_e32 v5, v3
	v_mov_b32_e32 v6, v3
	v_mov_b32_e32 v7, v3
	v_mov_b32_e32 v8, v3
	v_mov_b32_e32 v9, v3
	v_mov_b32_e32 v10, v3
	v_mov_b32_e32 v11, v3
	v_mov_b32_e32 v12, v3
	v_mov_b32_e32 v13, v3
	v_mov_b32_e32 v14, v3
	v_mov_b32_e32 v15, v3
	v_mov_b64_e32 v[32:33], v[16:17]
	v_mov_b64_e32 v[48:49], v[16:17]
	s_mov_b32 s3, 3
	s_lshl_b32 s4, s12, 6
	s_mov_b64 s[0:1], -1
	v_mov_b32_e32 v177, 0
	s_xor_b64 s[14:15], vcc, -1
	v_mov_b64_e32 v[30:31], v[14:15]
	v_mov_b64_e32 v[28:29], v[12:13]
	v_mov_b64_e32 v[26:27], v[10:11]
	v_mov_b64_e32 v[24:25], v[8:9]
	v_mov_b64_e32 v[22:23], v[6:7]
	v_mov_b64_e32 v[20:21], v[4:5]
	v_mov_b64_e32 v[18:19], v[2:3]
	v_mov_b64_e32 v[46:47], v[14:15]
	v_mov_b64_e32 v[44:45], v[12:13]
	v_mov_b64_e32 v[42:43], v[10:11]
	v_mov_b64_e32 v[40:41], v[8:9]
	v_mov_b64_e32 v[38:39], v[6:7]
	v_mov_b64_e32 v[36:37], v[4:5]
	v_mov_b64_e32 v[34:35], v[2:3]
	v_mov_b32_e32 v2, 0
	v_mov_b64_e32 v[228:229], 0
	v_mov_b64_e32 v[230:231], 0
	v_mov_b64_e32 v[232:233], 0
	v_mov_b64_e32 v[234:235], 0
	v_mov_b64_e32 v[236:237], 0
	v_mov_b64_e32 v[238:239], 0
	v_mov_b64_e32 v[240:241], 0
	v_mov_b64_e32 v[242:243], 0
	s_waitcnt vmcnt(0)
	v_add_u32_e32 v226, 0x3400, v184
	ds_write_b128 v201, v[106:109]
	ds_write_b128 v202, v[110:113]
	ds_write_b128 v203, v[114:117]
	ds_write2_b64 v226, v[118:119], v[120:121] offset1:1
	v_add_u32_e32 v226, 0x3400, v186
	ds_write2_b64 v226, v[130:131], v[132:133] offset1:1
	s_branch .LBB0_990

; template <int DQK, int MODE> ...
;     ...
;     if (it + 2 < ntile) gload(R, j + 2 * dir);
;     __builtin_amdgcn_sched_barrier(0);
;     if (active && j <= hiw && j >= low) {
;       const u16* Ks = lds + st * STG;
;       const u16* Vs = Ks + KT;
;       f32x16 S[2];
;       const bool far = (MODE == 1) && ((qpos0 + 32 * w) - (j * 64 + 63) >= 256);
;       const float cinit = (MODE != 2) ? (-m_run + (far ? btab[512] : 0.f)) : 0.f;
;       {
;         bf16x8 kf[2][NKK];
; #pragma unroll
;         for (int ku = 0; ku < 2; ++ku)
; #pragma unroll
;           for (int kk = 0; kk < NKK; ++kk)
;             kf[ku][kk] = *(const bf16x8*)(Ks + (ku * 32 + ql) * KST + kk * 16 + hh * 8);
;         __builtin_amdgcn_sched_barrier(0);
; #pragma unroll
;         for (int ku = 0; ku < 2; ++ku)
; #pragma unroll
;           for (int r = 0; r < 16; ++r) S[ku][r] = cinit;
; #pragma unroll
;         for (int kk = 0; kk < NKK; ++kk)
; #pragma unroll
;           for (int ku = 0; ku < 2; ++ku)
;             S[ku] = __builtin_amdgcn_mfma_f32_32x32x16_bf16(kf[ku][kk], qf[kk], S[ku], 0, 0, 0);
;       }
;     ...
;         float mx = -1e30f;
; #pragma unroll
;         for (int ku = 0; ku < 2; ++ku)
; #pragma unroll
;           for (int r = 0; r < 16; ++r) mx = fmaxf(mx, S[ku][r]);
;         if (__builtin_amdgcn_ballot_w64(first || mx > 6.f) != 0ull) {
.LBB0_990:
	v_add_u32_e32 v220, s4, v171
	v_add_u32_e32 v220, 0xfc000080, v220
	v_add_u32_e32 v222, s4, v173
	v_mad_i64_i32 v[220:221], s[6:7], v220, s85, v[178:179]
	v_add_u32_e32 v222, 0xfc000080, v222
	v_mad_i64_i32 v[222:223], s[6:7], v222, s85, v[180:181]
	v_add_u32_e32 v224, s4, v175
	v_add_u32_e32 v224, 0xfc000080, v224
	v_mad_i64_i32 v[224:225], s[6:7], v224, s85, v[182:183]
	v_lshl_add_u64 v[244:245], v[188:189], 0, s[10:11]
	v_add_co_u32_e32 v244, vcc, 0x4000, v244
	s_nop 1
	v_addc_co_u32_e32 v245, vcc, -2, v245, vcc
	v_lshl_add_u64 v[248:249], v[190:191], 0, s[10:11]
	v_add_co_u32_e32 v248, vcc, 0x4000, v248
	s_nop 1
	v_addc_co_u32_e32 v249, vcc, -2, v249, vcc
	s_add_i32 s5, s3, -1
	s_cmp_gt_i32 s5, s2
	s_waitcnt lgkmcnt(0)
	s_barrier
	s_cbranch_scc1 .LBB0_992
	global_load_dwordx4 v[106:109], v[220:221], off
	global_load_dwordx4 v[110:113], v[222:223], off
	global_load_dwordx4 v[114:117], v[224:225], off
	global_load_dwordx4 v[118:121], v[244:245], off
	global_load_dwordx4 v[130:133], v[248:249], off
.LBB0_992:
	s_add_i32 s6, s12, s3
	s_add_i32 s7, s6, 0xffeffffd
	v_cmp_le_i32_e32 vcc, s7, v199
	s_and_b64 s[16:17], s[14:15], vcc
	v_cmp_ge_u32_e32 vcc, s7, v200
	s_and_b64 s[18:19], s[16:17], vcc
	s_and_saveexec_b64 s[16:17], s[18:19]
	s_cbranch_execz .Lmy_ia0_a
	ds_read_b128 v[4:7], v185
	ds_read_b128 v[8:11], v185 offset:32
	ds_read_b128 v[12:15], v185 offset:64
	ds_read_b128 v[146:149], v185 offset:96
	ds_read_b128 v[150:153], v185 offset:128
	ds_read_b128 v[154:157], v185 offset:160
	ds_read_b128 v[158:161], v185 offset:6656
	ds_read_b128 v[162:165], v185 offset:6688
	ds_read_b128 v[204:207], v185 offset:6720
	ds_read_b128 v[208:211], v185 offset:6752
	ds_read_b128 v[212:215], v185 offset:6784
	ds_read_b128 v[216:219], v185 offset:6816
	s_waitcnt lgkmcnt(11)
	v_mfma_f32_32x32x16_bf16 v[66:81], v[4:7], v[86:89], v[228:243]
	v_add_u32_e32 v4, 0x3000, v187
	s_waitcnt lgkmcnt(5)
	v_mfma_f32_32x32x16_bf16 v[50:65], v[158:161], v[86:89], v[228:243]
	s_cmp_gt_i32 s5, s2
	s_cbranch_scc1 .Lmy_w1_nl
	v_add_u32_e32 v226, 0x8e00, v184
	s_waitcnt vmcnt(9)
	ds_write_b128 v201, v[122:125] offset:23040
	s_waitcnt vmcnt(8)
	ds_write_b128 v202, v[126:129] offset:23040
	s_waitcnt vmcnt(7)
	ds_write_b128 v203, v[134:137] offset:23040
	s_waitcnt vmcnt(6)
	ds_write2_b64 v226, v[138:139], v[140:141] offset1:1
	v_add_u32_e32 v226, 0x8e00, v186
	s_waitcnt vmcnt(5)
	ds_write2_b64 v226, v[142:143], v[144:145] offset1:1
	s_branch .Lmy_w1_dn
.Lmy_w1_nl:
	v_add_u32_e32 v226, 0x8e00, v184
	s_waitcnt vmcnt(4)
	ds_write_b128 v201, v[122:125] offset:23040
	s_waitcnt vmcnt(3)
	ds_write_b128 v202, v[126:129] offset:23040
	s_waitcnt vmcnt(2)
	ds_write_b128 v203, v[134:137] offset:23040
	s_waitcnt vmcnt(1)
	ds_write2_b64 v226, v[138:139], v[140:141] offset1:1
	v_add_u32_e32 v226, 0x8e00, v186
	s_waitcnt vmcnt(0)
	ds_write2_b64 v226, v[142:143], v[144:145] offset1:1
.Lmy_w1_dn:
	v_mfma_f32_32x32x16_bf16 v[66:81], v[8:11], v[82:85], v[66:81]
	s_waitcnt lgkmcnt(9)
	v_mfma_f32_32x32x16_bf16 v[50:65], v[162:165], v[82:85], v[50:65]
	ds_read2_b64 v[162:165], v4 offset0:128 offset1:130
	v_mfma_f32_32x32x16_bf16 v[66:81], v[12:15], v[94:97], v[66:81]
	s_waitcnt lgkmcnt(9)
	v_mfma_f32_32x32x16_bf16 v[50:65], v[204:207], v[94:97], v[50:65]
	v_mfma_f32_32x32x16_bf16 v[66:81], v[146:149], v[90:93], v[66:81]
	s_waitcnt lgkmcnt(8)
	v_mfma_f32_32x32x16_bf16 v[50:65], v[208:211], v[90:93], v[50:65]
	v_mfma_f32_32x32x16_bf16 v[66:81], v[150:153], v[102:105], v[66:81]
	s_waitcnt lgkmcnt(7)
	v_mfma_f32_32x32x16_bf16 v[50:65], v[212:215], v[102:105], v[50:65]
	v_mfma_f32_32x32x16_bf16 v[66:81], v[154:157], v[98:101], v[66:81]
	ds_read2_b64 v[154:157], v4 offset0:132 offset1:134
	ds_read2_b64 v[146:149], v4 offset0:136 offset1:138
	ds_read2_b64 v[8:11], v4 offset0:140 offset1:142
	v_add_u32_e32 v4, 0x4000, v187
	ds_read2_b64 v[158:161], v4 offset0:224 offset1:226
	ds_read2_b64 v[150:153], v4 offset0:228 offset1:230
	ds_read2_b64 v[12:15], v4 offset0:232 offset1:234
	ds_read2_b64 v[4:7], v4 offset0:236 offset1:238
	s_waitcnt lgkmcnt(13)
	v_mfma_f32_32x32x16_bf16 v[50:65], v[216:219], v[98:101], v[50:65]
	s_nop 1
	v_max3_f32 v16, v66, s38, v67
	v_max3_f32 v16, v16, v68, v69
	v_max3_f32 v16, v16, v70, v71
	v_max3_f32 v16, v16, v72, v73
	v_max3_f32 v16, v16, v74, v75
	v_max3_f32 v16, v16, v76, v77
	v_max3_f32 v16, v16, v78, v79
	v_max3_f32 v16, v16, v80, v81
	s_nop 1
	v_max3_f32 v16, v16, v50, v51
	v_max3_f32 v16, v16, v52, v53
	v_max3_f32 v16, v16, v54, v55
	v_max3_f32 v16, v16, v56, v57
	v_max3_f32 v16, v16, v58, v59
	v_max3_f32 v16, v16, v60, v61
	v_max3_f32 v16, v16, v62, v63
	v_max3_f32 v16, v16, v64, v65
	v_cmp_lt_f32_e32 vcc, s39, v16
	s_or_b64 vcc, s[0:1], vcc
	s_cbranch_vccz .LBB0_995
; template <int DQK, int MODE> ...
;     ...
;           mx = xhalf_max(mx);
;           const float d = first ? mx : (mx > 6.f ? mx : 0.f);
;           const float alpha = first ? 1.f : __builtin_amdgcn_exp2f(-d);
;           m_run += d;
;           lsum *= alpha;
; #pragma unroll
;           for (int ku = 0; ku < 2; ++ku)
; #pragma unroll
;             for (int r = 0; r < 16; ++r) S[ku][r] -= d;
; #pragma unroll
;           for (int du = 0; du < 2; ++du)
; #pragma unroll
;             for (int r = 0; r < 16; ++r) O[du][r] *= alpha;
;         }
;         first = false;
;         float rsum = 0.f;
; #pragma unroll
;         for (int ku = 0; ku < 2; ++ku)
; #pragma unroll
;           for (int r = 0; r < 16; ++r) {
;             float e = __builtin_amdgcn_exp2f(S[ku][r]);
;             S[ku][r] = e;
;             rsum += e;
;           }
;         lsum += rsum;
;     ...
; #pragma unroll
;       for (int s = 0; s < 4; ++s) {
;         const int ku = s >> 1, b = 8 * (s & 1);
;         u32x4 t;
;         t.x = pack2(S[ku][b + 0], S[ku][b + 1]);
;         t.y = pack2(S[ku][b + 2], S[ku][b + 3]);
;         t.z = pack2(S[ku][b + 4], S[ku][b + 5]);
;         t.w = pack2(S[ku][b + 6], S[ku][b + 7]);
;         pf[s] = __builtin_bit_cast(bf16x8, t);
;       }
;       if (MODE == 2) {
; #pragma unroll
;         for (int du = 0; du < 2; ++du)
; #pragma unroll
;           for (int s4 = 0; s4 < 4; ++s4) {
;             const u16* vp = Vs + (du * 32 + ql) * VST + 16 * s4 + 4 * hh;
;             u32x2 a = *(const u32x2*)vp;
;             u32x2 b = *(const u32x2*)(vp + 8);
;             vf[du][s4] = (u32x4){a.x, a.y, b.x, b.y};
;           }
;       }
; #pragma unroll
;       for (int s4 = 0; s4 < 4; ++s4)
; #pragma unroll
;         for (int du = 0; du < 2; ++du)
;           O[du] = __builtin_amdgcn_mfma_f32_32x32x16_bf16(__builtin_bit_cast(bf16x8, vf[du][s4]), pf[s4], O[du], 0, 0, 0);
	v_mov_b32_e32 v17, v16
	s_nop 1
	v_permlane32_swap_b32_e32 v16, v17
	v_max_f32_e32 v17, v17, v17
	v_max_f32_e32 v16, v16, v16
	v_max_f32_e32 v16, v16, v17
	v_cmp_lt_f32_e32 vcc, s39, v16
	s_or_b64 vcc, s[0:1], vcc
	s_nop 0
	v_cndmask_b32_e32 v16, 0, v16, vcc
	v_exp_f32_e64 v17, -v16
	v_add_f32_e32 v2, v2, v16
	v_sub_f32_e32 v228, 0, v2
	v_mov_b32_e32 v229, v228
	v_mov_b32_e32 v230, v228
	v_mov_b32_e32 v231, v228
	v_mov_b32_e32 v232, v228
	v_mov_b32_e32 v233, v228
	v_mov_b32_e32 v234, v228
	v_mov_b32_e32 v235, v228
	v_mov_b32_e32 v236, v228
	v_mov_b32_e32 v237, v228
	v_mov_b32_e32 v238, v228
	v_mov_b32_e32 v239, v228
	v_mov_b32_e32 v240, v228
	v_mov_b32_e32 v241, v228
	v_mov_b32_e32 v242, v228
	v_mov_b32_e32 v243, v228
	v_cndmask_b32_e64 v204, v17, 1.0, s[0:1]
	v_mul_f32_e32 v177, v177, v204
	v_pk_add_f32 v[66:67], v[66:67], v[16:17] op_sel_hi:[1,0] neg_lo:[0,1] neg_hi:[0,1]
	v_pk_add_f32 v[68:69], v[68:69], v[16:17] op_sel_hi:[1,0] neg_lo:[0,1] neg_hi:[0,1]
	v_pk_add_f32 v[70:71], v[70:71], v[16:17] op_sel_hi:[1,0] neg_lo:[0,1] neg_hi:[0,1]
	v_pk_add_f32 v[72:73], v[72:73], v[16:17] op_sel_hi:[1,0] neg_lo:[0,1] neg_hi:[0,1]
	v_pk_add_f32 v[74:75], v[74:75], v[16:17] op_sel_hi:[1,0] neg_lo:[0,1] neg_hi:[0,1]
	v_pk_add_f32 v[76:77], v[76:77], v[16:17] op_sel_hi:[1,0] neg_lo:[0,1] neg_hi:[0,1]
	v_pk_add_f32 v[78:79], v[78:79], v[16:17] op_sel_hi:[1,0] neg_lo:[0,1] neg_hi:[0,1]
	v_pk_add_f32 v[80:81], v[80:81], v[16:17] op_sel_hi:[1,0] neg_lo:[0,1] neg_hi:[0,1]
	v_pk_add_f32 v[50:51], v[50:51], v[16:17] op_sel_hi:[1,0] neg_lo:[0,1] neg_hi:[0,1]
	v_pk_add_f32 v[52:53], v[52:53], v[16:17] op_sel_hi:[1,0] neg_lo:[0,1] neg_hi:[0,1]
	v_pk_add_f32 v[54:55], v[54:55], v[16:17] op_sel_hi:[1,0] neg_lo:[0,1] neg_hi:[0,1]
	v_pk_add_f32 v[56:57], v[56:57], v[16:17] op_sel_hi:[1,0] neg_lo:[0,1] neg_hi:[0,1]
	v_pk_add_f32 v[58:59], v[58:59], v[16:17] op_sel_hi:[1,0] neg_lo:[0,1] neg_hi:[0,1]
	v_pk_add_f32 v[60:61], v[60:61], v[16:17] op_sel_hi:[1,0] neg_lo:[0,1] neg_hi:[0,1]
	v_pk_add_f32 v[62:63], v[62:63], v[16:17] op_sel_hi:[1,0] neg_lo:[0,1] neg_hi:[0,1]
	v_pk_add_f32 v[64:65], v[64:65], v[16:17] op_sel_hi:[1,0] neg_lo:[0,1] neg_hi:[0,1]
	v_pk_mul_f32 v[48:49], v[48:49], v[204:205] op_sel_hi:[1,0]
	v_pk_mul_f32 v[46:47], v[46:47], v[204:205] op_sel_hi:[1,0]
	v_pk_mul_f32 v[44:45], v[44:45], v[204:205] op_sel_hi:[1,0]
	v_pk_mul_f32 v[42:43], v[42:43], v[204:205] op_sel_hi:[1,0]
	v_pk_mul_f32 v[40:41], v[40:41], v[204:205] op_sel_hi:[1,0]
	v_pk_mul_f32 v[38:39], v[38:39], v[204:205] op_sel_hi:[1,0]
	v_pk_mul_f32 v[36:37], v[36:37], v[204:205] op_sel_hi:[1,0]
	v_pk_mul_f32 v[34:35], v[34:35], v[204:205] op_sel_hi:[1,0]
	v_pk_mul_f32 v[32:33], v[32:33], v[204:205] op_sel_hi:[1,0]
	v_pk_mul_f32 v[30:31], v[30:31], v[204:205] op_sel_hi:[1,0]
	v_pk_mul_f32 v[28:29], v[28:29], v[204:205] op_sel_hi:[1,0]
	v_pk_mul_f32 v[26:27], v[26:27], v[204:205] op_sel_hi:[1,0]
	v_pk_mul_f32 v[24:25], v[24:25], v[204:205] op_sel_hi:[1,0]
	v_pk_mul_f32 v[22:23], v[22:23], v[204:205] op_sel_hi:[1,0]
	v_pk_mul_f32 v[20:21], v[20:21], v[204:205] op_sel_hi:[1,0]
	v_pk_mul_f32 v[18:19], v[18:19], v[204:205] op_sel_hi:[1,0]
.LBB0_995:
	v_exp_f32_e32 v16, v66
	v_exp_f32_e32 v66, v67
	v_exp_f32_e32 v67, v68
	v_exp_f32_e32 v68, v69
	v_add_f32_e32 v17, 0, v16
	v_exp_f32_e32 v69, v70
	v_add_f32_e32 v17, v66, v17
	v_exp_f32_e32 v70, v71
	v_add_f32_e32 v17, v67, v17
	v_exp_f32_e32 v71, v72
	v_add_f32_e32 v17, v68, v17
	v_exp_f32_e32 v72, v73
	v_add_f32_e32 v17, v69, v17
	v_exp_f32_e32 v73, v74
	v_add_f32_e32 v17, v70, v17
	v_exp_f32_e32 v74, v75
	v_add_f32_e32 v17, v71, v17
	v_exp_f32_e32 v75, v76
	v_add_f32_e32 v17, v72, v17
	v_exp_f32_e32 v76, v77
	v_exp_f32_e32 v77, v78
	v_exp_f32_e32 v78, v79
	v_exp_f32_e32 v79, v80
	v_exp_f32_e32 v80, v81
	v_exp_f32_e32 v81, v50
	v_exp_f32_e32 v204, v51
	v_exp_f32_e32 v205, v52
	v_exp_f32_e32 v206, v53
	v_cvt_pk_bf16_f32 v50, v16, v66
	v_cvt_pk_bf16_f32 v51, v67, v68
	v_cvt_pk_bf16_f32 v52, v69, v70
	v_cvt_pk_bf16_f32 v53, v71, v72
	v_add_f32_e32 v17, v73, v17
	v_add_f32_e32 v17, v74, v17
	s_waitcnt lgkmcnt(7)
	v_mfma_f32_32x32x16_bf16 v[34:49], v[162:165], v[50:53], v[34:49]
	v_add_f32_e32 v17, v75, v17
	v_add_f32_e32 v17, v76, v17
	v_add_f32_e32 v17, v77, v17
	v_add_f32_e32 v17, v78, v17
	v_add_f32_e32 v17, v79, v17
	v_add_f32_e32 v17, v80, v17
	v_exp_f32_e32 v207, v54
	s_waitcnt lgkmcnt(3)
	v_mfma_f32_32x32x16_bf16 v[18:33], v[158:161], v[50:53], v[18:33]
	v_exp_f32_e32 v208, v55
	v_exp_f32_e32 v209, v56
	v_exp_f32_e32 v210, v57
	v_cvt_pk_bf16_f32 v54, v73, v74
	v_cvt_pk_bf16_f32 v55, v75, v76
	v_cvt_pk_bf16_f32 v56, v77, v78
	v_cvt_pk_bf16_f32 v57, v79, v80
	v_add_f32_e32 v17, v81, v17
	v_add_f32_e32 v17, v204, v17
	v_mfma_f32_32x32x16_bf16 v[34:49], v[154:157], v[54:57], v[34:49]
	v_add_f32_e32 v17, v205, v17
	v_add_f32_e32 v17, v206, v17
	v_add_f32_e32 v17, v207, v17
	v_exp_f32_e32 v211, v58
	v_add_f32_e32 v17, v208, v17
	v_exp_f32_e32 v212, v59
	v_add_f32_e32 v17, v209, v17
	s_waitcnt lgkmcnt(2)
	v_mfma_f32_32x32x16_bf16 v[18:33], v[150:153], v[54:57], v[18:33]
	v_exp_f32_e32 v213, v60
	v_add_f32_e32 v17, v210, v17
	v_exp_f32_e32 v214, v61
	v_cvt_pk_bf16_f32 v58, v81, v204
	v_cvt_pk_bf16_f32 v59, v205, v206
	v_cvt_pk_bf16_f32 v60, v207, v208
	v_cvt_pk_bf16_f32 v61, v209, v210
	v_add_f32_e32 v17, v211, v17
	v_exp_f32_e32 v215, v62
	v_mfma_f32_32x32x16_bf16 v[34:49], v[146:149], v[58:61], v[34:49]
	v_add_f32_e32 v17, v212, v17
	v_exp_f32_e32 v216, v63
	v_add_f32_e32 v17, v213, v17
	v_exp_f32_e32 v217, v64
	v_add_f32_e32 v17, v214, v17
	v_exp_f32_e32 v65, v65
	v_add_f32_e32 v17, v215, v17
	s_waitcnt lgkmcnt(1)
	v_mfma_f32_32x32x16_bf16 v[18:33], v[12:15], v[58:61], v[18:33]
	v_add_f32_e32 v17, v216, v17
	v_add_f32_e32 v17, v217, v17
	v_add_f32_e32 v17, v65, v17
	v_cvt_pk_bf16_f32 v62, v211, v212
	v_cvt_pk_bf16_f32 v63, v213, v214
	v_cvt_pk_bf16_f32 v64, v215, v216
	v_cvt_pk_bf16_f32 v65, v217, v65
	v_add_f32_e32 v177, v177, v17
	s_andn2_b64 s[0:1], s[0:1], exec
	v_mfma_f32_32x32x16_bf16 v[34:49], v[8:11], v[62:65], v[34:49]
	s_waitcnt lgkmcnt(0)
	v_mfma_f32_32x32x16_bf16 v[18:33], v[4:7], v[62:65], v[18:33]
	s_branch .LBB0_996
.Lmy_ia0_a:
	s_or_b64 exec, exec, s[16:17]
	s_cmp_gt_i32 s5, s2
	s_cbranch_scc1 .Lmy_w3_nl
	v_add_u32_e32 v226, 0x8e00, v184
	s_waitcnt vmcnt(9)
	ds_write_b128 v201, v[122:125] offset:23040
	s_waitcnt vmcnt(8)
	ds_write_b128 v202, v[126:129] offset:23040
	s_waitcnt vmcnt(7)
	ds_write_b128 v203, v[134:137] offset:23040
	s_waitcnt vmcnt(6)
	ds_write2_b64 v226, v[138:139], v[140:141] offset1:1
	v_add_u32_e32 v226, 0x8e00, v186
	s_waitcnt vmcnt(5)
	ds_write2_b64 v226, v[142:143], v[144:145] offset1:1
	s_branch .Lmy_w3_dn

; template <int DQK, int MODE> ...
;     ...
;   auto step = [&](TRegs& R, int it) -> bool {
;     const int j = jstart + dir * it;
;     const int st = it & 1;
;     lstore(R, st);
;     if (MODE == 2) {
;       int alive = (carry != 0.f) ? 1 : 0;
;       if (!__syncthreads_or(alive)) return false;
;     } else {
;       __syncthreads();
;     }
;     if (it + 2 < ntile) gload(R, j + 2 * dir);
;     __builtin_amdgcn_sched_barrier(0);
;     if (active && j <= hiw && j >= low) {
;       const u16* Ks = lds + st * STG;
;       const u16* Vs = Ks + KT;
;       f32x16 S[2];
;       const bool far = (MODE == 1) && ((qpos0 + 32 * w) - (j * 64 + 63) >= 256);
;       const float cinit = (MODE != 2) ? (-m_run + (far ? btab[512] : 0.f)) : 0.f;
;       {
;         bf16x8 kf[2][NKK];
; #pragma unroll
;         for (int ku = 0; ku < 2; ++ku)
; #pragma unroll
;           for (int kk = 0; kk < NKK; ++kk)
;             kf[ku][kk] = *(const bf16x8*)(Ks + (ku * 32 + ql) * KST + kk * 16 + hh * 8);
;         __builtin_amdgcn_sched_barrier(0);
; #pragma unroll
;         for (int ku = 0; ku < 2; ++ku)
; #pragma unroll
;           for (int r = 0; r < 16; ++r) S[ku][r] = cinit;
; #pragma unroll
;         for (int kk = 0; kk < NKK; ++kk)
; #pragma unroll
;           for (int ku = 0; ku < 2; ++ku)
;             S[ku] = __builtin_amdgcn_mfma_f32_32x32x16_bf16(kf[ku][kk], qf[kk], S[ku], 0, 0, 0);
;       }
.Lmy_w3_dn:
.LBB0_996:
	s_or_b64 exec, exec, s[16:17]
	s_add_i32 s7, s3, -3
	s_cmp_ge_i32 s7, s2
	s_cbranch_scc1 .LBB0_989
	v_add_u32_e32 v220, s4, v171
	v_add_u32_e32 v220, 0xfc0000c0, v220
	v_add_u32_e32 v222, s4, v173
	v_mad_i64_i32 v[220:221], s[16:17], v220, s85, v[178:179]
	v_add_u32_e32 v222, 0xfc0000c0, v222
	v_mad_i64_i32 v[222:223], s[16:17], v222, s85, v[180:181]
	v_add_u32_e32 v224, s4, v175
	v_add_u32_e32 v224, 0xfc0000c0, v224
	v_mad_i64_i32 v[224:225], s[16:17], v224, s85, v[182:183]
	v_lshl_add_u64 v[244:245], v[188:189], 0, s[10:11]
	v_add_co_u32_e32 v244, vcc, 0x6000, v244
	s_nop 1
	v_addc_co_u32_e32 v245, vcc, -2, v245, vcc
	v_lshl_add_u64 v[248:249], v[190:191], 0, s[10:11]
	v_add_co_u32_e32 v248, vcc, 0x6000, v248
	s_nop 1
	v_addc_co_u32_e32 v249, vcc, -2, v249, vcc
	s_cmp_gt_i32 s3, s2
	s_waitcnt lgkmcnt(0)
	s_barrier
	s_cbranch_scc1 .LBB0_999
	global_load_dwordx4 v[122:125], v[220:221], off
	global_load_dwordx4 v[126:129], v[222:223], off
	global_load_dwordx4 v[134:137], v[224:225], off
	global_load_dwordx4 v[138:141], v[244:245], off
	global_load_dwordx4 v[142:145], v[248:249], off
.LBB0_999:
	s_add_i32 s13, s6, 0xffeffffe
	v_cmp_le_i32_e32 vcc, s13, v199
	s_and_b64 s[6:7], s[14:15], vcc
	v_cmp_ge_u32_e32 vcc, s13, v200
	s_and_b64 s[6:7], s[6:7], vcc
	s_and_saveexec_b64 s[16:17], s[6:7]
	s_cbranch_execz .Lmy_ia1_a
	ds_read_b128 v[4:7], v185 offset:23040
	ds_read_b128 v[8:11], v185 offset:23072
	ds_read_b128 v[12:15], v185 offset:23104
	ds_read_b128 v[146:149], v185 offset:23136
	ds_read_b128 v[150:153], v185 offset:23168
	ds_read_b128 v[154:157], v185 offset:23200
	ds_read_b128 v[158:161], v185 offset:29696
	ds_read_b128 v[162:165], v185 offset:29728
	ds_read_b128 v[204:207], v185 offset:29760
	ds_read_b128 v[208:211], v185 offset:29792
	ds_read_b128 v[212:215], v185 offset:29824
	ds_read_b128 v[216:219], v185 offset:29856
	s_waitcnt lgkmcnt(11)
	v_mfma_f32_32x32x16_bf16 v[66:81], v[4:7], v[86:89], v[228:243]
	v_add_u32_e32 v4, 0x8800, v187
	s_waitcnt lgkmcnt(5)
	v_mfma_f32_32x32x16_bf16 v[50:65], v[158:161], v[86:89], v[228:243]
	s_cmp_gt_i32 s3, s2
	s_cbranch_scc1 .Lmy_w2_nl
	v_add_u32_e32 v226, 0x3400, v184
	s_waitcnt vmcnt(9)
	ds_write_b128 v201, v[106:109]
	s_waitcnt vmcnt(8)
	ds_write_b128 v202, v[110:113]
	s_waitcnt vmcnt(7)
	ds_write_b128 v203, v[114:117]
	s_waitcnt vmcnt(6)
	ds_write2_b64 v226, v[118:119], v[120:121] offset1:1
	v_add_u32_e32 v226, 0x3400, v186
	s_waitcnt vmcnt(5)
	ds_write2_b64 v226, v[130:131], v[132:133] offset1:1
	s_branch .Lmy_w2_dn
.Lmy_w2_nl:
	v_add_u32_e32 v226, 0x3400, v184
	s_waitcnt vmcnt(4)
	ds_write_b128 v201, v[106:109]
	s_waitcnt vmcnt(3)
	ds_write_b128 v202, v[110:113]
	s_waitcnt vmcnt(2)
	ds_write_b128 v203, v[114:117]
	s_waitcnt vmcnt(1)
	ds_write2_b64 v226, v[118:119], v[120:121] offset1:1
	v_add_u32_e32 v226, 0x3400, v186
	s_waitcnt vmcnt(0)
	ds_write2_b64 v226, v[130:131], v[132:133] offset1:1
; template <int DQK, int MODE> ...
;     ...
;         for (int kk = 0; kk < NKK; ++kk)
; #pragma unroll
;           for (int ku = 0; ku < 2; ++ku)
;             S[ku] = __builtin_amdgcn_mfma_f32_32x32x16_bf16(kf[ku][kk], qf[kk], S[ku], 0, 0, 0);
;       }
;       u32x4 vf[2][4];
;       if (MODE != 2) {
; #pragma unroll
;         for (int du = 0; du < 2; ++du)
; #pragma unroll
;           for (int s4 = 0; s4 < 4; ++s4) {
;             const u16* vp = Vs + (du * 32 + ql) * VST + 16 * s4 + 4 * hh;
;             u32x2 a = *(const u32x2*)vp;
;             u32x2 b = *(const u32x2*)(vp + 8);
;             vf[du][s4] = (u32x4){a.x, a.y, b.x, b.y};
;           }
;         __builtin_amdgcn_sched_barrier(0);
;       }
;       bf16x8 pf[4];
;       if (MODE != 2) {
;         if (MODE == 1 && !far) {
;           const bool noclip = ((qpos0 + 32 * w + 31) - j * 64 <= 256) && ((qpos0 + 32 * w) - (j * 64 + 63) >= -256);
;           if (noclip) {
;             const float* bt = btab + 256 + qpos - j * 64;
; #pragma unroll
;             for (int ku = 0; ku < 2; ++ku)
; #pragma unroll
;               for (int r = 0; r < 16; ++r) S[ku][r] += bt[-(32 * ku + (r & 3) + 8 * (r >> 2) + 4 * hh)];
;           } else {
; #pragma unroll
;             for (int ku = 0; ku < 2; ++ku)
; #pragma unroll
;               for (int r = 0; r < 16; ++r) {
;                 int key = 32 * ku + (r & 3) + 8 * (r >> 2) + 4 * hh;
;                 int rel = qpos - (j * 64 + key);
;                 rel = min(256, max(-256, rel)) + 256;
;                 S[ku][r] += btab[rel];
;               }
;           }
;         }
;         float mx = -1e30f;
; #pragma unroll
;         for (int ku = 0; ku < 2; ++ku)
; #pragma unroll
;           for (int r = 0; r < 16; ++r) mx = fmaxf(mx, S[ku][r]);
;         if (__builtin_amdgcn_ballot_w64(first || mx > 6.f) != 0ull) {
;           mx = xhalf_max(mx);
;           const float d = first ? mx : (mx > 6.f ? mx : 0.f);
;           const float alpha = first ? 1.f : __builtin_amdgcn_exp2f(-d);
;           m_run += d;
;           lsum *= alpha;
; #pragma unroll
;           for (int ku = 0; ku < 2; ++ku)
; #pragma unroll
;             for (int r = 0; r < 16; ++r) S[ku][r] -= d;
; #pragma unroll
;           for (int du = 0; du < 2; ++du)
; #pragma unroll
;             for (int r = 0; r < 16; ++r) O[du][r] *= alpha;
;         }
.Lmy_w2_dn:
	v_mfma_f32_32x32x16_bf16 v[66:81], v[8:11], v[82:85], v[66:81]
	s_waitcnt lgkmcnt(9)
	v_mfma_f32_32x32x16_bf16 v[50:65], v[162:165], v[82:85], v[50:65]
	ds_read2_b64 v[162:165], v4 offset0:192 offset1:194
	v_mfma_f32_32x32x16_bf16 v[66:81], v[12:15], v[94:97], v[66:81]
	s_waitcnt lgkmcnt(9)
	v_mfma_f32_32x32x16_bf16 v[50:65], v[204:207], v[94:97], v[50:65]
	v_mfma_f32_32x32x16_bf16 v[66:81], v[146:149], v[90:93], v[66:81]
	s_waitcnt lgkmcnt(8)
	v_mfma_f32_32x32x16_bf16 v[50:65], v[208:211], v[90:93], v[50:65]
	v_mfma_f32_32x32x16_bf16 v[66:81], v[150:153], v[102:105], v[66:81]
	s_waitcnt lgkmcnt(7)
	v_mfma_f32_32x32x16_bf16 v[50:65], v[212:215], v[102:105], v[50:65]
	v_mfma_f32_32x32x16_bf16 v[66:81], v[154:157], v[98:101], v[66:81]
	ds_read2_b64 v[154:157], v4 offset0:196 offset1:198
	ds_read2_b64 v[146:149], v4 offset0:200 offset1:202
	ds_read2_b64 v[8:11], v4 offset0:204 offset1:206
	v_add_u32_e32 v4, 0xa000, v187
	ds_read2_b64 v[158:161], v4 offset0:32 offset1:34
	ds_read2_b64 v[150:153], v4 offset0:36 offset1:38
	ds_read2_b64 v[12:15], v4 offset0:40 offset1:42
	ds_read2_b64 v[4:7], v4 offset0:44 offset1:46
	s_waitcnt lgkmcnt(13)
	v_mfma_f32_32x32x16_bf16 v[50:65], v[216:219], v[98:101], v[50:65]
	s_nop 1
	v_max3_f32 v16, v66, s38, v67
	v_max3_f32 v16, v16, v68, v69
	v_max3_f32 v16, v16, v70, v71
	v_max3_f32 v16, v16, v72, v73
	v_max3_f32 v16, v16, v74, v75
	v_max3_f32 v16, v16, v76, v77
	v_max3_f32 v16, v16, v78, v79
	v_max3_f32 v16, v16, v80, v81
	s_nop 1
	v_max3_f32 v16, v16, v50, v51
	v_max3_f32 v16, v16, v52, v53
	v_max3_f32 v16, v16, v54, v55
	v_max3_f32 v16, v16, v56, v57
	v_max3_f32 v16, v16, v58, v59
	v_max3_f32 v16, v16, v60, v61
	v_max3_f32 v16, v16, v62, v63
	v_max3_f32 v16, v16, v64, v65
	v_cmp_lt_f32_e32 vcc, s39, v16
	s_or_b64 vcc, s[0:1], vcc
	s_cbranch_vccz .LBB0_987
	v_mov_b32_e32 v17, v16
	s_nop 1
	v_permlane32_swap_b32_e32 v16, v17
	v_max_f32_e32 v17, v17, v17
	v_max_f32_e32 v16, v16, v16
	v_max_f32_e32 v16, v16, v17
	v_cmp_lt_f32_e32 vcc, s39, v16
	s_or_b64 vcc, s[0:1], vcc
	s_nop 0
	v_cndmask_b32_e32 v16, 0, v16, vcc
	v_exp_f32_e64 v17, -v16
	v_add_f32_e32 v2, v2, v16
	v_sub_f32_e32 v228, 0, v2
	v_mov_b32_e32 v229, v228
	v_mov_b32_e32 v230, v228
	v_mov_b32_e32 v231, v228
	v_mov_b32_e32 v232, v228
	v_mov_b32_e32 v233, v228
	v_mov_b32_e32 v234, v228
	v_mov_b32_e32 v235, v228
	v_mov_b32_e32 v236, v228
	v_mov_b32_e32 v237, v228
	v_mov_b32_e32 v238, v228
	v_mov_b32_e32 v239, v228
	v_mov_b32_e32 v240, v228
	v_mov_b32_e32 v241, v228
	v_mov_b32_e32 v242, v228
	v_mov_b32_e32 v243, v228
	v_cndmask_b32_e64 v204, v17, 1.0, s[0:1]
	v_mul_f32_e32 v177, v177, v204
	v_pk_add_f32 v[66:67], v[66:67], v[16:17] op_sel_hi:[1,0] neg_lo:[0,1] neg_hi:[0,1]
	v_pk_add_f32 v[68:69], v[68:69], v[16:17] op_sel_hi:[1,0] neg_lo:[0,1] neg_hi:[0,1]
	v_pk_add_f32 v[70:71], v[70:71], v[16:17] op_sel_hi:[1,0] neg_lo:[0,1] neg_hi:[0,1]
	v_pk_add_f32 v[72:73], v[72:73], v[16:17] op_sel_hi:[1,0] neg_lo:[0,1] neg_hi:[0,1]
	v_pk_add_f32 v[74:75], v[74:75], v[16:17] op_sel_hi:[1,0] neg_lo:[0,1] neg_hi:[0,1]
	v_pk_add_f32 v[76:77], v[76:77], v[16:17] op_sel_hi:[1,0] neg_lo:[0,1] neg_hi:[0,1]
	v_pk_add_f32 v[78:79], v[78:79], v[16:17] op_sel_hi:[1,0] neg_lo:[0,1] neg_hi:[0,1]
	v_pk_add_f32 v[80:81], v[80:81], v[16:17] op_sel_hi:[1,0] neg_lo:[0,1] neg_hi:[0,1]
	v_pk_add_f32 v[50:51], v[50:51], v[16:17] op_sel_hi:[1,0] neg_lo:[0,1] neg_hi:[0,1]
	v_pk_add_f32 v[52:53], v[52:53], v[16:17] op_sel_hi:[1,0] neg_lo:[0,1] neg_hi:[0,1]
	v_pk_add_f32 v[54:55], v[54:55], v[16:17] op_sel_hi:[1,0] neg_lo:[0,1] neg_hi:[0,1]
	v_pk_add_f32 v[56:57], v[56:57], v[16:17] op_sel_hi:[1,0] neg_lo:[0,1] neg_hi:[0,1]
	v_pk_add_f32 v[58:59], v[58:59], v[16:17] op_sel_hi:[1,0] neg_lo:[0,1] neg_hi:[0,1]
	v_pk_add_f32 v[60:61], v[60:61], v[16:17] op_sel_hi:[1,0] neg_lo:[0,1] neg_hi:[0,1]
	v_pk_add_f32 v[62:63], v[62:63], v[16:17] op_sel_hi:[1,0] neg_lo:[0,1] neg_hi:[0,1]
	v_pk_add_f32 v[64:65], v[64:65], v[16:17] op_sel_hi:[1,0] neg_lo:[0,1] neg_hi:[0,1]
	v_pk_mul_f32 v[48:49], v[48:49], v[204:205] op_sel_hi:[1,0]
	v_pk_mul_f32 v[46:47], v[46:47], v[204:205] op_sel_hi:[1,0]
	v_pk_mul_f32 v[44:45], v[44:45], v[204:205] op_sel_hi:[1,0]
	v_pk_mul_f32 v[42:43], v[42:43], v[204:205] op_sel_hi:[1,0]
	v_pk_mul_f32 v[40:41], v[40:41], v[204:205] op_sel_hi:[1,0]
	v_pk_mul_f32 v[38:39], v[38:39], v[204:205] op_sel_hi:[1,0]
	v_pk_mul_f32 v[36:37], v[36:37], v[204:205] op_sel_hi:[1,0]
	v_pk_mul_f32 v[34:35], v[34:35], v[204:205] op_sel_hi:[1,0]
	v_pk_mul_f32 v[32:33], v[32:33], v[204:205] op_sel_hi:[1,0]
	v_pk_mul_f32 v[30:31], v[30:31], v[204:205] op_sel_hi:[1,0]
	v_pk_mul_f32 v[28:29], v[28:29], v[204:205] op_sel_hi:[1,0]
	v_pk_mul_f32 v[26:27], v[26:27], v[204:205] op_sel_hi:[1,0]
	v_pk_mul_f32 v[24:25], v[24:25], v[204:205] op_sel_hi:[1,0]
	v_pk_mul_f32 v[22:23], v[22:23], v[204:205] op_sel_hi:[1,0]
	v_pk_mul_f32 v[20:21], v[20:21], v[204:205] op_sel_hi:[1,0]
	v_pk_mul_f32 v[18:19], v[18:19], v[204:205] op_sel_hi:[1,0]
	s_branch .LBB0_987
.Lmy_ia1_a:
	s_or_b64 exec, exec, s[16:17]
	s_cmp_gt_i32 s3, s2
	s_cbranch_scc1 .Lmy_w4_nl
	v_add_u32_e32 v226, 0x3400, v184
	s_waitcnt vmcnt(9)
	ds_write_b128 v201, v[106:109]
	s_waitcnt vmcnt(8)
	ds_write_b128 v202, v[110:113]
	s_waitcnt vmcnt(7)
	ds_write_b128 v203, v[114:117]
	s_waitcnt vmcnt(6)
	ds_write2_b64 v226, v[118:119], v[120:121] offset1:1
	v_add_u32_e32 v226, 0x3400, v186
	s_waitcnt vmcnt(5)
	ds_write2_b64 v226, v[130:131], v[132:133] offset1:1
	s_branch .Lmy_w4_dn

; template <int DQK, int MODE> ...
;     ...
;   if (active) {
;     if (MODE != 2) {
;       float lt = lsum + __shfl_xor(lsum, 32);
;       float inv = 1.f / lt;
; #pragma unroll
;       for (int du = 0; du < 2; ++du)
; #pragma unroll
;         for (int r = 0; r < 16; ++r) O[du][r] *= inv;
;     }
;     float ss = 0.f;
; #pragma unroll
;     for (int du = 0; du < 2; ++du)
; #pragma unroll
;       for (int r = 0; r < 16; ++r) ss += O[du][r] * O[du][r];
;     ss += __shfl_xor(ss, 32);
;     const float rstd = rsqrtf(ss * (1.f / 64.f) + EPS);
;     const long m = (long)mrow0 + 32 * w + ql;
;     const float* og = p.out_g + l * 1024 + colbase;
;     const u16* gt = p.gates + m * 1024 + colbase;
;     u16* yo = p.xn + m * 1024 + colbase;
.LBB0_1002:
	s_waitcnt lgkmcnt(0)
	s_ashr_i32 s35, s34, 31
	s_and_saveexec_b64 s[0:1], s[8:9]
	s_xor_b64 s[0:1], exec, s[0:1]
	s_cbranch_execz .LBB0_1004
	v_and_b32_e32 v4, 64, v195
	v_xor_b32_e32 v2, 32, v195
	v_add_u32_e32 v4, 64, v4
	v_cmp_lt_i32_e32 vcc, v2, v4
	s_load_dwordx8 s[12:19], s[28:29], 0x180
	v_mov_b32_e32 v173, v3
	v_cndmask_b32_e32 v2, v195, v2, vcc
	v_lshlrev_b32_e32 v78, 2, v2
	ds_bpermute_b32 v2, v78, v177
	v_ashrrev_i32_e32 v175, 31, v174
	v_lshl_add_u64 v[4:5], v[172:173], 0, s[34:35]
	s_mov_b32 s25, s37
	v_lshl_add_u64 v[4:5], v[4:5], 0, v[174:175]
	s_waitcnt lgkmcnt(0)
	v_add_f32_e32 v2, v177, v2
	v_div_scale_f32 v6, s[2:3], v2, v2, 1.0
	s_lshl_b64 s[2:3], s[24:25], 2
	s_add_u32 s8, s44, s2
	v_lshlrev_b64 v[16:17], 11, v[4:5]
	s_addc_u32 s9, s45, s3
	v_lshl_add_u64 v[4:5], s[16:17], 0, v[16:17]
	s_lshl_b64 s[10:11], s[24:25], 1
	v_lshl_add_u64 v[4:5], v[4:5], 0, s[10:11]
	v_mov_b32_e32 v177, v3
	v_lshl_add_u64 v[4:5], v[4:5], 0, v[176:177]
	global_load_dwordx2 v[50:51], v[4:5], off
	global_load_dwordx4 v[12:15], v170, s[8:9]
	v_rcp_f32_e32 v7, v6
	s_mov_b32 s2, 0x800000
	v_lshl_add_u64 v[16:17], s[60:61], 0, v[16:17]
	v_lshl_add_u64 v[16:17], v[16:17], 0, s[10:11]
	v_fma_f32 v8, -v6, v7, 1.0
	v_fmac_f32_e32 v7, v8, v7
	v_div_scale_f32 v8, vcc, 1.0, v2, 1.0
	v_mul_f32_e32 v9, v8, v7
	v_fma_f32 v10, -v6, v9, v8
	v_fmac_f32_e32 v9, v10, v7
	v_fma_f32 v6, -v6, v9, v8
	v_div_fmas_f32 v6, v6, v7, v9
	v_div_fixup_f32 v2, v6, v2, 1.0
	v_pk_mul_f32 v[34:35], v[34:35], v[2:3] op_sel_hi:[1,0]
	v_pk_mul_f32 v[36:37], v[36:37], v[2:3] op_sel_hi:[1,0]
	v_pk_mul_f32 v[54:55], v[34:35], v[34:35]
	v_pk_mul_f32 v[10:11], v[28:29], v[2:3] op_sel_hi:[1,0]
	v_pk_mul_f32 v[8:9], v[30:31], v[2:3] op_sel_hi:[1,0]
	v_pk_mul_f32 v[6:7], v[32:33], v[2:3] op_sel_hi:[1,0]
	v_pk_mul_f32 v[52:53], v[36:37], v[36:37]
	v_pk_mul_f32 v[40:41], v[40:41], v[2:3] op_sel_hi:[1,0]
	v_pk_mul_f32 v[38:39], v[38:39], v[2:3] op_sel_hi:[1,0]
	v_pk_mul_f32 v[44:45], v[44:45], v[2:3] op_sel_hi:[1,0]
	v_pk_mul_f32 v[42:43], v[42:43], v[2:3] op_sel_hi:[1,0]
	v_pk_mul_f32 v[48:49], v[48:49], v[2:3] op_sel_hi:[1,0]
	v_pk_mul_f32 v[46:47], v[46:47], v[2:3] op_sel_hi:[1,0]
	v_pk_mul_f32 v[20:21], v[20:21], v[2:3] op_sel_hi:[1,0]
	v_pk_mul_f32 v[18:19], v[18:19], v[2:3] op_sel_hi:[1,0]
	v_pk_mul_f32 v[24:25], v[24:25], v[2:3] op_sel_hi:[1,0]
	v_pk_mul_f32 v[22:23], v[22:23], v[2:3] op_sel_hi:[1,0]
	v_pk_mul_f32 v[26:27], v[26:27], v[2:3] op_sel_hi:[1,0]
	v_add_f32_e32 v2, v54, v55
	v_add_f32_e32 v2, v52, v2
	v_pk_mul_f32 v[58:59], v[38:39], v[38:39]
	v_add_f32_e32 v2, v53, v2
	v_add_f32_e32 v2, v58, v2
	v_pk_mul_f32 v[56:57], v[40:41], v[40:41]
	v_add_f32_e32 v2, v59, v2
	v_add_f32_e32 v2, v56, v2
	v_pk_mul_f32 v[62:63], v[42:43], v[42:43]
	v_add_f32_e32 v2, v57, v2
	v_add_f32_e32 v2, v62, v2
	v_pk_mul_f32 v[60:61], v[44:45], v[44:45]
	v_add_f32_e32 v2, v63, v2
	v_add_f32_e32 v2, v60, v2
	v_pk_mul_f32 v[66:67], v[46:47], v[46:47]
	v_add_f32_e32 v2, v61, v2
	v_add_f32_e32 v2, v66, v2
	v_pk_mul_f32 v[64:65], v[48:49], v[48:49]
	v_add_f32_e32 v2, v67, v2
	v_add_f32_e32 v2, v64, v2
	v_pk_mul_f32 v[70:71], v[18:19], v[18:19]
	v_add_f32_e32 v2, v65, v2
	v_add_f32_e32 v2, v70, v2
	v_pk_mul_f32 v[68:69], v[20:21], v[20:21]
	v_add_f32_e32 v2, v71, v2
	v_add_f32_e32 v2, v68, v2
	v_pk_mul_f32 v[74:75], v[22:23], v[22:23]
	v_add_f32_e32 v2, v69, v2
	v_add_f32_e32 v2, v74, v2
	v_pk_mul_f32 v[72:73], v[24:25], v[24:25]
	v_add_f32_e32 v2, v75, v2
	v_add_f32_e32 v2, v72, v2
	v_pk_mul_f32 v[76:77], v[26:27], v[26:27]
	v_add_f32_e32 v2, v73, v2
	v_add_f32_e32 v2, v76, v2
	v_pk_mul_f32 v[28:29], v[10:11], v[10:11]
	v_add_f32_e32 v2, v77, v2
	v_add_f32_e32 v2, v28, v2
	v_pk_mul_f32 v[30:31], v[8:9], v[8:9]
	v_add_f32_e32 v2, v29, v2
	v_add_f32_e32 v2, v30, v2
	v_pk_mul_f32 v[32:33], v[6:7], v[6:7]
	v_add_f32_e32 v2, v31, v2
	v_add_f32_e32 v2, v32, v2
	v_add_f32_e32 v2, v33, v2
	ds_bpermute_b32 v30, v78, v2
	s_waitcnt vmcnt(1)
	v_and_b32_e32 v31, 0xffff0000, v50
	v_lshlrev_b32_e32 v28, 16, v51
	v_and_b32_e32 v29, 0xffff0000, v51
	v_lshl_add_u64 v[16:17], v[16:17], 0, v[176:177]
	s_waitcnt lgkmcnt(0)
	v_add_f32_e32 v2, v2, v30
	v_fmamk_f32 v2, v2, 0x3c800000, v193
	v_mul_f32_e32 v30, 0x4b800000, v2
	v_cmp_gt_f32_e32 vcc, s2, v2
	s_nop 1
	v_cndmask_b32_e32 v2, v2, v30, vcc
	v_rsq_f32_e32 v2, v2
	v_lshlrev_b32_e32 v30, 16, v50
	v_mul_f32_e32 v32, 0x45800000, v2
	v_cndmask_b32_e32 v2, v2, v32, vcc
	v_pk_mul_f32 v[32:33], v[34:35], v[2:3] op_sel_hi:[1,0]
	v_pk_mul_f32 v[18:19], v[18:19], v[2:3] op_sel_hi:[1,0]
	s_waitcnt vmcnt(0)
; template <int DQK, int MODE> ...
;     ...
; #pragma unroll
;     for (int du = 0; du < 2; ++du)
; #pragma unroll
;       for (int c = 0; c < 4; ++c) {
;         const int d0 = 32 * du + 8 * c + 4 * hh;
;         u32x2 g2 = *(const u32x2*)(gt + d0);
;         f32x4 o4 = *(const f32x4*)(og + d0);
;         float y0 = O[du][4 * c + 0] * rstd * o4.x * __uint_as_float(g2.x << 16);
;         float y1 = O[du][4 * c + 1] * rstd * o4.y * __uint_as_float(g2.x & 0xffff0000u);
;         float y2 = O[du][4 * c + 2] * rstd * o4.z * __uint_as_float(g2.y << 16);
;         float y3 = O[du][4 * c + 3] * rstd * o4.w * __uint_as_float(g2.y & 0xffff0000u);
;         u32x2 o = {pack2(y0, y1), pack2(y2, y3)};
;         *(u32x2*)(yo + d0) = o;
;       }
	v_pk_mul_f32 v[12:13], v[12:13], v[32:33]
	v_pk_mul_f32 v[32:33], v[40:41], v[2:3] op_sel_hi:[1,0]
	v_pk_mul_f32 v[12:13], v[12:13], v[30:31]
	v_pk_mul_f32 v[30:31], v[36:37], v[2:3] op_sel_hi:[1,0]
	v_cvt_pk_bf16_f32 v12, v12, v13
	v_pk_mul_f32 v[14:15], v[14:15], v[30:31]
	v_pk_mul_f32 v[30:31], v[38:39], v[2:3] op_sel_hi:[1,0]
	v_pk_mul_f32 v[14:15], v[14:15], v[28:29]
	v_pk_mul_f32 v[20:21], v[20:21], v[2:3] op_sel_hi:[1,0]
	v_cvt_pk_bf16_f32 v13, v14, v15
	global_store_dwordx2 v[16:17], v[12:13], off
	global_load_dwordx4 v[12:15], v170, s[8:9] offset:32
	s_nop 0
	global_load_dwordx2 v[28:29], v[4:5], off offset:16
	v_pk_mul_f32 v[10:11], v[10:11], v[2:3] op_sel_hi:[1,0]
	v_pk_mul_f32 v[8:9], v[8:9], v[2:3] op_sel_hi:[1,0]
	v_pk_mul_f32 v[6:7], v[6:7], v[2:3] op_sel_hi:[1,0]
	s_waitcnt vmcnt(1)
	v_pk_mul_f32 v[12:13], v[12:13], v[30:31]
	s_waitcnt vmcnt(0)
	v_lshlrev_b32_e32 v30, 16, v28
	v_and_b32_e32 v31, 0xffff0000, v28
	v_pk_mul_f32 v[14:15], v[14:15], v[32:33]
	v_lshlrev_b32_e32 v28, 16, v29
	v_and_b32_e32 v29, 0xffff0000, v29
	v_pk_mul_f32 v[12:13], v[12:13], v[30:31]
	v_pk_mul_f32 v[14:15], v[14:15], v[28:29]
	v_cvt_pk_bf16_f32 v12, v12, v13
	v_cvt_pk_bf16_f32 v13, v14, v15
	global_store_dwordx2 v[16:17], v[12:13], off offset:16
	global_load_dwordx4 v[12:15], v170, s[8:9] offset:64
	s_nop 0
	global_load_dwordx2 v[28:29], v[4:5], off offset:32
	v_pk_mul_f32 v[30:31], v[42:43], v[2:3] op_sel_hi:[1,0]
	v_pk_mul_f32 v[32:33], v[44:45], v[2:3] op_sel_hi:[1,0]
	s_waitcnt vmcnt(1)
	v_pk_mul_f32 v[12:13], v[12:13], v[30:31]
	s_waitcnt vmcnt(0)
	v_lshlrev_b32_e32 v30, 16, v28
	v_and_b32_e32 v31, 0xffff0000, v28
	v_pk_mul_f32 v[14:15], v[14:15], v[32:33]
	v_lshlrev_b32_e32 v28, 16, v29
	v_and_b32_e32 v29, 0xffff0000, v29
	v_pk_mul_f32 v[12:13], v[12:13], v[30:31]
	v_pk_mul_f32 v[14:15], v[14:15], v[28:29]
	v_cvt_pk_bf16_f32 v12, v12, v13
	v_cvt_pk_bf16_f32 v13, v14, v15
	global_store_dwordx2 v[16:17], v[12:13], off offset:32
	global_load_dwordx4 v[12:15], v170, s[8:9] offset:96
	s_nop 0
	global_load_dwordx2 v[28:29], v[4:5], off offset:48
	v_pk_mul_f32 v[30:31], v[46:47], v[2:3] op_sel_hi:[1,0]
	v_pk_mul_f32 v[32:33], v[48:49], v[2:3] op_sel_hi:[1,0]
	s_waitcnt vmcnt(1)
	v_pk_mul_f32 v[12:13], v[12:13], v[30:31]
	s_waitcnt vmcnt(0)
	v_lshlrev_b32_e32 v30, 16, v28
	v_and_b32_e32 v31, 0xffff0000, v28
	v_pk_mul_f32 v[14:15], v[14:15], v[32:33]
	v_lshlrev_b32_e32 v28, 16, v29
	v_and_b32_e32 v29, 0xffff0000, v29
	v_pk_mul_f32 v[12:13], v[12:13], v[30:31]
	v_pk_mul_f32 v[14:15], v[14:15], v[28:29]
	v_cvt_pk_bf16_f32 v12, v12, v13
	v_cvt_pk_bf16_f32 v13, v14, v15
	global_store_dwordx2 v[16:17], v[12:13], off offset:48
	global_load_dwordx4 v[12:15], v170, s[8:9] offset:128
	s_nop 0
	global_load_dwordx2 v[28:29], v[4:5], off offset:64
	s_waitcnt vmcnt(1)
	v_pk_mul_f32 v[12:13], v[12:13], v[18:19]
	s_waitcnt vmcnt(0)
	v_lshlrev_b32_e32 v18, 16, v28
	v_and_b32_e32 v19, 0xffff0000, v28
	v_pk_mul_f32 v[14:15], v[14:15], v[20:21]
	v_lshlrev_b32_e32 v20, 16, v29
	v_and_b32_e32 v21, 0xffff0000, v29
	v_pk_mul_f32 v[12:13], v[12:13], v[18:19]
	v_pk_mul_f32 v[14:15], v[14:15], v[20:21]
	v_cvt_pk_bf16_f32 v12, v12, v13
	v_cvt_pk_bf16_f32 v13, v14, v15
	global_store_dwordx2 v[16:17], v[12:13], off offset:64
	global_load_dwordx4 v[12:15], v170, s[8:9] offset:160
	s_nop 0
	global_load_dwordx2 v[18:19], v[4:5], off offset:80
	v_pk_mul_f32 v[20:21], v[22:23], v[2:3] op_sel_hi:[1,0]
	v_pk_mul_f32 v[22:23], v[24:25], v[2:3] op_sel_hi:[1,0]
	s_waitcnt vmcnt(1)
	v_pk_mul_f32 v[12:13], v[12:13], v[20:21]
	s_waitcnt vmcnt(0)
	v_lshlrev_b32_e32 v20, 16, v18
	v_and_b32_e32 v21, 0xffff0000, v18
	v_pk_mul_f32 v[14:15], v[14:15], v[22:23]
	v_lshlrev_b32_e32 v18, 16, v19
	v_and_b32_e32 v19, 0xffff0000, v19
	v_pk_mul_f32 v[12:13], v[12:13], v[20:21]
	v_pk_mul_f32 v[14:15], v[14:15], v[18:19]
	v_cvt_pk_bf16_f32 v12, v12, v13
	v_cvt_pk_bf16_f32 v13, v14, v15
	global_store_dwordx2 v[16:17], v[12:13], off offset:80
	global_load_dwordx4 v[12:15], v170, s[8:9] offset:192
	s_nop 0
	global_load_dwordx2 v[18:19], v[4:5], off offset:96
	v_pk_mul_f32 v[20:21], v[26:27], v[2:3] op_sel_hi:[1,0]
	s_waitcnt vmcnt(1)
	v_pk_mul_f32 v[10:11], v[14:15], v[10:11]
	v_pk_mul_f32 v[12:13], v[12:13], v[20:21]
	s_waitcnt vmcnt(0)
	v_lshlrev_b32_e32 v20, 16, v18
	v_and_b32_e32 v21, 0xffff0000, v18
	v_lshlrev_b32_e32 v14, 16, v19
	v_and_b32_e32 v15, 0xffff0000, v19
	v_pk_mul_f32 v[12:13], v[12:13], v[20:21]
	v_pk_mul_f32 v[10:11], v[10:11], v[14:15]
	v_cvt_pk_bf16_f32 v12, v12, v13
	v_cvt_pk_bf16_f32 v13, v10, v11
	global_store_dwordx2 v[16:17], v[12:13], off offset:96
	global_load_dwordx4 v[10:13], v170, s[8:9] offset:224
	s_nop 0
	global_load_dwordx2 v[4:5], v[4:5], off offset:112
	s_waitcnt vmcnt(1)
	v_pk_mul_f32 v[8:9], v[10:11], v[8:9]
	s_waitcnt vmcnt(0)
	v_lshlrev_b32_e32 v10, 16, v4
	v_and_b32_e32 v11, 0xffff0000, v4
	v_pk_mul_f32 v[6:7], v[12:13], v[6:7]
	v_lshlrev_b32_e32 v4, 16, v5
	v_and_b32_e32 v5, 0xffff0000, v5
	v_pk_mul_f32 v[8:9], v[8:9], v[10:11]
	v_pk_mul_f32 v[4:5], v[6:7], v[4:5]
	v_cvt_pk_bf16_f32 v6, v8, v9
	v_cvt_pk_bf16_f32 v7, v4, v5
	global_store_dwordx2 v[16:17], v[6:7], off offset:112

; template <int DQK, int MODE> ...
;     ...
;   auto lstore = [&](const TRegs& R, int st) {
;     u16* Ks = lds + st * STG;
;     u16* Vs = Ks + KT;
; #pragma unroll
;     for (int i = 0; i < NKL; ++i) {
;       int c = tid + i * 256;
;       int row = c / KCH, cc = c % KCH;
;       *(u32x4*)(Ks + row * KST + cc * 8) = R.k[i];
;     }
; #pragma unroll
;     for (int i = 0; i < 2; ++i) {
;       int c = tid + i * 256;
;       int d = c >> 3, cc = c & 7;
;       u32x2 lo = {R.v[i].x, R.v[i].y}, hi = {R.v[i].z, R.v[i].w};
;       *(u32x2*)(Vs + d * VST + cc * 8) = lo;
;       *(u32x2*)(Vs + d * VST + cc * 8 + 4) = hi;
;     }
;   };
;   f32x16 O[2];
; #pragma unroll
;   for (int du = 0; du < 2; ++du)
; #pragma unroll
;     for (int r = 0; r < 16; ++r) O[du][r] = 0.f;
;   float m_run = 0.f, lsum = 0.f;
;   bool first = true;
;   float carry = active ? 1.f : 0.f;
;   const int dir = (MODE == 2) ? -1 : 1;
;   const int jstart = (MODE == 2) ? jhi : jlo;
;   const int ntile = jhi - jlo + 1;
;   auto step = [&](TRegs& R, int it) -> bool {
;     const int j = jstart + dir * it;
;     const int st = it & 1;
;     lstore(R, st);
;     if (MODE == 2) {
;       int alive = (carry != 0.f) ? 1 : 0;
;       if (!__syncthreads_or(alive)) return false;
;     } else {
;       __syncthreads();
;     }
;     if (it + 2 < ntile) gload(R, j + 2 * dir);
.LBB0_2122:
	v_lshlrev_b32_e32 v174, 3, v13
	v_mov_b32_e32 v47, 0
	s_cmp_lt_i32 s9, 0xfff00000
	v_mov_b32_e32 v46, 0
	v_mov_b32_e32 v45, 0
	v_mov_b32_e32 v44, 0
	v_mov_b32_e32 v43, 0
	v_mov_b32_e32 v42, 0
	v_mov_b32_e32 v41, 0
	v_mov_b32_e32 v40, 0
	v_mov_b32_e32 v39, 0
	v_mov_b32_e32 v38, 0
	v_mov_b32_e32 v37, 0
	v_mov_b32_e32 v36, 0
	v_mov_b32_e32 v35, 0
	v_mov_b32_e32 v34, 0
	v_mov_b32_e32 v33, 0
	v_mov_b32_e32 v32, 0
	v_mov_b32_e32 v31, 0
	v_mov_b32_e32 v30, 0
	v_mov_b32_e32 v29, 0
	v_mov_b32_e32 v28, 0
	v_mov_b32_e32 v27, 0
	v_mov_b32_e32 v26, 0
	v_mov_b32_e32 v25, 0
	v_mov_b32_e32 v24, 0
	v_mov_b32_e32 v23, 0
	v_mov_b32_e32 v22, 0
	v_mov_b32_e32 v21, 0
	v_mov_b32_e32 v20, 0
	v_mov_b32_e32 v19, 0
	v_mov_b32_e32 v18, 0
	v_mov_b32_e32 v17, 0
	v_mov_b32_e32 v16, 0
	v_mov_b32_e32 v175, 0
	s_cbranch_scc1 .LBB0_2139
	v_lshl_add_u64 v[176:177], v[2:3], 1, s[12:13]
	v_ashrrev_i32_e32 v3, 7, v12
	v_cndmask_b32_e64 v3, 0, v3, s[46:47]
	v_add_u32_e32 v197, s14, v3
	v_max_i32_e32 v3, 0x100000, v197
	s_movk_i32 s9, 0xd0
	v_add_u32_e32 v199, 0xfff00000, v3
	v_mul_lo_u32 v3, v169, s9
	v_lshl_add_u32 v200, v2, 1, v3
	v_mul_lo_u32 v2, v171, s9
	v_lshl_add_u32 v201, v4, 1, v2
	v_mul_lo_u32 v2, v173, s9
	v_lshl_add_u32 v202, v8, 1, v2
	v_lshrrev_b32_e32 v2, 3, v12
	v_lshl_add_u64 v[178:179], v[4:5], 1, s[12:13]
	v_lshl_add_u64 v[180:181], v[8:9], 1, s[12:13]
	v_mad_u64_u32 v[182:183], s[12:13], v2, s95, v[0:1]
	v_lshrrev_b32_e32 v2, 3, v14
	v_mad_u64_u32 v[184:185], s[12:13], v2, s95, v[0:1]
	v_lshlrev_b32_e32 v0, 1, v174
	v_mul_u32_u24_e32 v2, 0x68, v170
	v_lshl_add_u32 v183, v2, 1, v0
	v_sub_u32_e32 v0, v0, v174
	v_mul_u32_u24_e32 v2, 0x4c, v170
	s_mov_b32 s9, s19
	v_lshl_add_u32 v185, v2, 1, v0
	s_lshl_b64 s[12:13], s[8:9], 13
	v_and_b32_e32 v0, 7, v12
	v_lshl_or_b32 v2, v0, 4, s12
	v_mov_b32_e32 v3, s13
	v_lshl_add_u64 v[4:5], v[6:7], 1, v[2:3]
	v_lshl_add_u64 v[2:3], v[10:11], 1, v[2:3]
	v_mov_b32_e32 v14, v1
	v_mov_b32_e32 v15, v1
	v_lshl_add_u64 v[186:187], s[10:11], 0, v[4:5]
	v_lshl_add_u64 v[188:189], s[10:11], 0, v[2:3]
	v_mov_b32_e32 v0, v1
	v_mov_b32_e32 v2, v1
	v_mov_b32_e32 v3, v1
	v_mov_b32_e32 v4, v1
	v_mov_b32_e32 v5, v1
	v_mov_b32_e32 v6, v1
	v_mov_b32_e32 v7, v1
	v_mov_b32_e32 v8, v1
	v_mov_b32_e32 v9, v1
	v_mov_b32_e32 v10, v1
	v_mov_b32_e32 v11, v1
	v_mov_b32_e32 v12, v1
	v_mov_b32_e32 v13, v1
	v_mov_b64_e32 v[30:31], v[14:15]
	v_mov_b64_e32 v[46:47], v[14:15]
	s_mov_b32 s17, 3
	s_lshl_b32 s9, s8, 6
	s_mov_b64 s[10:11], -1
	v_mov_b32_e32 v175, 0
	s_xor_b64 s[12:13], vcc, -1
	v_mov_b64_e32 v[28:29], v[12:13]
	v_mov_b64_e32 v[26:27], v[10:11]
	v_mov_b64_e32 v[24:25], v[8:9]
	v_mov_b64_e32 v[22:23], v[6:7]
	v_mov_b64_e32 v[20:21], v[4:5]
	v_mov_b64_e32 v[18:19], v[2:3]
	v_mov_b64_e32 v[16:17], v[0:1]
	v_mov_b64_e32 v[44:45], v[12:13]
	v_mov_b64_e32 v[42:43], v[10:11]
	v_mov_b64_e32 v[40:41], v[8:9]
	v_mov_b64_e32 v[38:39], v[6:7]
	v_mov_b64_e32 v[36:37], v[4:5]
	v_mov_b64_e32 v[34:35], v[2:3]
	v_mov_b64_e32 v[32:33], v[0:1]
	v_mov_b32_e32 v0, 0
	v_mov_b64_e32 v[228:229], 0
	v_mov_b64_e32 v[230:231], 0
	v_mov_b64_e32 v[232:233], 0
	v_mov_b64_e32 v[234:235], 0
	v_mov_b64_e32 v[236:237], 0
	v_mov_b64_e32 v[238:239], 0
	v_mov_b64_e32 v[240:241], 0
	v_mov_b64_e32 v[242:243], 0
	s_waitcnt vmcnt(0)
	v_add_u32_e32 v226, 0x3400, v182
	ds_write_b128 v200, v[104:107]
	ds_write_b128 v201, v[108:111]
	ds_write_b128 v202, v[112:115]
	ds_write2_b64 v226, v[116:117], v[118:119] offset1:1
	v_add_u32_e32 v226, 0x3400, v184
	ds_write2_b64 v226, v[128:129], v[130:131] offset1:1
	s_branch .LBB0_2127

; template <int DQK, int MODE> ...
;     ...
;     if (it + 2 < ntile) gload(R, j + 2 * dir);
;     __builtin_amdgcn_sched_barrier(0);
;     if (active && j <= hiw && j >= low) {
;       const u16* Ks = lds + st * STG;
;       const u16* Vs = Ks + KT;
;       f32x16 S[2];
;       const bool far = (MODE == 1) && ((qpos0 + 32 * w) - (j * 64 + 63) >= 256);
;       const float cinit = (MODE != 2) ? (-m_run + (far ? btab[512] : 0.f)) : 0.f;
;       {
;         bf16x8 kf[2][NKK];
; #pragma unroll
;         for (int ku = 0; ku < 2; ++ku)
; #pragma unroll
;           for (int kk = 0; kk < NKK; ++kk)
;             kf[ku][kk] = *(const bf16x8*)(Ks + (ku * 32 + ql) * KST + kk * 16 + hh * 8);
;         __builtin_amdgcn_sched_barrier(0);
; #pragma unroll
;         for (int ku = 0; ku < 2; ++ku)
; #pragma unroll
;           for (int r = 0; r < 16; ++r) S[ku][r] = cinit;
; #pragma unroll
;         for (int kk = 0; kk < NKK; ++kk)
; #pragma unroll
;           for (int ku = 0; ku < 2; ++ku)
;             S[ku] = __builtin_amdgcn_mfma_f32_32x32x16_bf16(kf[ku][kk], qf[kk], S[ku], 0, 0, 0);
;       }
;     ...
;         float mx = -1e30f;
; #pragma unroll
;         for (int ku = 0; ku < 2; ++ku)
; #pragma unroll
;           for (int r = 0; r < 16; ++r) mx = fmaxf(mx, S[ku][r]);
;         if (__builtin_amdgcn_ballot_w64(first || mx > 6.f) != 0ull) {
.LBB0_2127:
	v_add_u32_e32 v220, s9, v169
	v_add_u32_e32 v220, 0xfc000080, v220
	v_add_u32_e32 v222, s9, v171
	v_mad_i64_i32 v[220:221], s[14:15], v220, s87, v[176:177]
	v_add_u32_e32 v222, 0xfc000080, v222
	v_mad_i64_i32 v[222:223], s[14:15], v222, s87, v[178:179]
	v_add_u32_e32 v224, s9, v173
	v_add_u32_e32 v224, 0xfc000080, v224
	v_mad_i64_i32 v[224:225], s[14:15], v224, s87, v[180:181]
	v_lshl_add_u64 v[244:245], v[186:187], 0, s[2:3]
	v_add_co_u32_e32 v244, vcc, 0x4000, v244
	s_nop 1
	v_addc_co_u32_e32 v245, vcc, -2, v245, vcc
	v_lshl_add_u64 v[248:249], v[188:189], 0, s[2:3]
	v_add_co_u32_e32 v248, vcc, 0x4000, v248
	s_nop 1
	v_addc_co_u32_e32 v249, vcc, -2, v249, vcc
	s_add_i32 s18, s17, -1
	s_cmp_gt_i32 s18, s16
	s_waitcnt lgkmcnt(0)
	s_barrier
	s_cbranch_scc1 .LBB0_2129
	global_load_dwordx4 v[104:107], v[220:221], off
	global_load_dwordx4 v[108:111], v[222:223], off
	global_load_dwordx4 v[112:115], v[224:225], off
	global_load_dwordx4 v[116:119], v[244:245], off
	global_load_dwordx4 v[128:131], v[248:249], off
.LBB0_2129:
	s_add_i32 s21, s8, s17
	s_add_i32 s30, s21, 0xffeffffd
	v_cmp_le_i32_e32 vcc, s30, v197
	s_and_b64 s[14:15], s[12:13], vcc
	v_cmp_ge_u32_e32 vcc, s30, v199
	s_and_b64 s[30:31], s[14:15], vcc
	s_and_saveexec_b64 s[14:15], s[30:31]
	s_cbranch_execz .Lmy_ia0_b
	ds_read_b128 v[2:5], v183
	ds_read_b128 v[6:9], v183 offset:32
	ds_read_b128 v[10:13], v183 offset:64
	ds_read_b128 v[144:147], v183 offset:96
	ds_read_b128 v[148:151], v183 offset:128
	ds_read_b128 v[152:155], v183 offset:160
	ds_read_b128 v[156:159], v183 offset:6656
	ds_read_b128 v[160:163], v183 offset:6688
	ds_read_b128 v[204:207], v183 offset:6720
	ds_read_b128 v[208:211], v183 offset:6752
	ds_read_b128 v[212:215], v183 offset:6784
	ds_read_b128 v[216:219], v183 offset:6816
	s_waitcnt lgkmcnt(11)
	v_mfma_f32_32x32x16_bf16 v[64:79], v[2:5], v[84:87], v[228:243]
	v_add_u32_e32 v2, 0x3000, v185
	s_waitcnt lgkmcnt(5)
	v_mfma_f32_32x32x16_bf16 v[48:63], v[156:159], v[84:87], v[228:243]
	s_cmp_gt_i32 s18, s16
	s_cbranch_scc1 .Lmy_w5_nl
	v_add_u32_e32 v226, 0x8e00, v182
	s_waitcnt vmcnt(9)
	ds_write_b128 v200, v[120:123] offset:23040
	s_waitcnt vmcnt(8)
	ds_write_b128 v201, v[124:127] offset:23040
	s_waitcnt vmcnt(7)
	ds_write_b128 v202, v[132:135] offset:23040
	s_waitcnt vmcnt(6)
	ds_write2_b64 v226, v[136:137], v[138:139] offset1:1
	v_add_u32_e32 v226, 0x8e00, v184
	s_waitcnt vmcnt(5)
	ds_write2_b64 v226, v[140:141], v[142:143] offset1:1
	s_branch .Lmy_w5_dn
.Lmy_w5_nl:
	v_add_u32_e32 v226, 0x8e00, v182
	s_waitcnt vmcnt(4)
	ds_write_b128 v200, v[120:123] offset:23040
	s_waitcnt vmcnt(3)
	ds_write_b128 v201, v[124:127] offset:23040
	s_waitcnt vmcnt(2)
	ds_write_b128 v202, v[132:135] offset:23040
	s_waitcnt vmcnt(1)
	ds_write2_b64 v226, v[136:137], v[138:139] offset1:1
	v_add_u32_e32 v226, 0x8e00, v184
	s_waitcnt vmcnt(0)
	ds_write2_b64 v226, v[140:141], v[142:143] offset1:1
.Lmy_w5_dn:
	v_mfma_f32_32x32x16_bf16 v[64:79], v[6:9], v[80:83], v[64:79]
	s_waitcnt lgkmcnt(9)
	v_mfma_f32_32x32x16_bf16 v[48:63], v[160:163], v[80:83], v[48:63]
	ds_read2_b64 v[160:163], v2 offset0:128 offset1:130
	v_mfma_f32_32x32x16_bf16 v[64:79], v[10:13], v[92:95], v[64:79]
	s_waitcnt lgkmcnt(9)
	v_mfma_f32_32x32x16_bf16 v[48:63], v[204:207], v[92:95], v[48:63]
	v_mfma_f32_32x32x16_bf16 v[64:79], v[144:147], v[88:91], v[64:79]
	s_waitcnt lgkmcnt(8)
	v_mfma_f32_32x32x16_bf16 v[48:63], v[208:211], v[88:91], v[48:63]
	v_mfma_f32_32x32x16_bf16 v[64:79], v[148:151], v[100:103], v[64:79]
	s_waitcnt lgkmcnt(7)
	v_mfma_f32_32x32x16_bf16 v[48:63], v[212:215], v[100:103], v[48:63]
	v_mfma_f32_32x32x16_bf16 v[64:79], v[152:155], v[96:99], v[64:79]
	ds_read2_b64 v[152:155], v2 offset0:132 offset1:134
	ds_read2_b64 v[144:147], v2 offset0:136 offset1:138
	ds_read2_b64 v[6:9], v2 offset0:140 offset1:142
	v_add_u32_e32 v2, 0x4000, v185
	ds_read2_b64 v[156:159], v2 offset0:224 offset1:226
	ds_read2_b64 v[148:151], v2 offset0:228 offset1:230
	ds_read2_b64 v[10:13], v2 offset0:232 offset1:234
	ds_read2_b64 v[2:5], v2 offset0:236 offset1:238
	s_waitcnt lgkmcnt(13)
	v_mfma_f32_32x32x16_bf16 v[48:63], v[216:219], v[96:99], v[48:63]
	s_nop 1
	v_max3_f32 v14, v64, s96, v65
	v_max3_f32 v14, v14, v66, v67
	v_max3_f32 v14, v14, v68, v69
	v_max3_f32 v14, v14, v70, v71
	v_max3_f32 v14, v14, v72, v73
	v_max3_f32 v14, v14, v74, v75
	v_max3_f32 v14, v14, v76, v77
	v_max3_f32 v14, v14, v78, v79
	s_nop 1
	v_max3_f32 v14, v14, v48, v49
	v_max3_f32 v14, v14, v50, v51
	v_max3_f32 v14, v14, v52, v53
	v_max3_f32 v14, v14, v54, v55
	v_max3_f32 v14, v14, v56, v57
	v_max3_f32 v14, v14, v58, v59
	v_max3_f32 v14, v14, v60, v61
	v_max3_f32 v14, v14, v62, v63
	v_cmp_lt_f32_e32 vcc, s97, v14
	s_or_b64 vcc, s[10:11], vcc
	s_cbranch_vccz .LBB0_2132
; template <int DQK, int MODE> ...
;     ...
;           mx = xhalf_max(mx);
;           const float d = first ? mx : (mx > 6.f ? mx : 0.f);
;           const float alpha = first ? 1.f : __builtin_amdgcn_exp2f(-d);
;           m_run += d;
;           lsum *= alpha;
; #pragma unroll
;           for (int ku = 0; ku < 2; ++ku)
; #pragma unroll
;             for (int r = 0; r < 16; ++r) S[ku][r] -= d;
; #pragma unroll
;           for (int du = 0; du < 2; ++du)
; #pragma unroll
;             for (int r = 0; r < 16; ++r) O[du][r] *= alpha;
;         }
;         first = false;
;         float rsum = 0.f;
; #pragma unroll
;         for (int ku = 0; ku < 2; ++ku)
; #pragma unroll
;           for (int r = 0; r < 16; ++r) {
;             float e = __builtin_amdgcn_exp2f(S[ku][r]);
;             S[ku][r] = e;
;             rsum += e;
;           }
;         lsum += rsum;
;     ...
; #pragma unroll
;       for (int s = 0; s < 4; ++s) {
;         const int ku = s >> 1, b = 8 * (s & 1);
;         u32x4 t;
;         t.x = pack2(S[ku][b + 0], S[ku][b + 1]);
;         t.y = pack2(S[ku][b + 2], S[ku][b + 3]);
;         t.z = pack2(S[ku][b + 4], S[ku][b + 5]);
;         t.w = pack2(S[ku][b + 6], S[ku][b + 7]);
;         pf[s] = __builtin_bit_cast(bf16x8, t);
;       }
;       if (MODE == 2) {
; #pragma unroll
;         for (int du = 0; du < 2; ++du)
; #pragma unroll
;           for (int s4 = 0; s4 < 4; ++s4) {
;             const u16* vp = Vs + (du * 32 + ql) * VST + 16 * s4 + 4 * hh;
;             u32x2 a = *(const u32x2*)vp;
;             u32x2 b = *(const u32x2*)(vp + 8);
;             vf[du][s4] = (u32x4){a.x, a.y, b.x, b.y};
;           }
;       }
; #pragma unroll
;       for (int s4 = 0; s4 < 4; ++s4)
; #pragma unroll
;         for (int du = 0; du < 2; ++du)
;           O[du] = __builtin_amdgcn_mfma_f32_32x32x16_bf16(__builtin_bit_cast(bf16x8, vf[du][s4]), pf[s4], O[du], 0, 0, 0);
	v_mov_b32_e32 v15, v14
	s_nop 1
	v_permlane32_swap_b32_e32 v14, v15
	v_max_f32_e32 v15, v15, v15
	v_max_f32_e32 v14, v14, v14
	v_max_f32_e32 v14, v14, v15
	v_cmp_lt_f32_e32 vcc, s97, v14
	s_or_b64 vcc, s[10:11], vcc
	s_nop 0
	v_cndmask_b32_e32 v14, 0, v14, vcc
	v_exp_f32_e64 v15, -v14
	v_add_f32_e32 v0, v0, v14
	v_sub_f32_e32 v228, 0, v0
	v_mov_b32_e32 v229, v228
	v_mov_b32_e32 v230, v228
	v_mov_b32_e32 v231, v228
	v_mov_b32_e32 v232, v228
	v_mov_b32_e32 v233, v228
	v_mov_b32_e32 v234, v228
	v_mov_b32_e32 v235, v228
	v_mov_b32_e32 v236, v228
	v_mov_b32_e32 v237, v228
	v_mov_b32_e32 v238, v228
	v_mov_b32_e32 v239, v228
	v_mov_b32_e32 v240, v228
	v_mov_b32_e32 v241, v228
	v_mov_b32_e32 v242, v228
	v_mov_b32_e32 v243, v228
	v_cndmask_b32_e64 v204, v15, 1.0, s[10:11]
	v_mul_f32_e32 v175, v175, v204
	v_pk_add_f32 v[64:65], v[64:65], v[14:15] op_sel_hi:[1,0] neg_lo:[0,1] neg_hi:[0,1]
	v_pk_add_f32 v[66:67], v[66:67], v[14:15] op_sel_hi:[1,0] neg_lo:[0,1] neg_hi:[0,1]
	v_pk_add_f32 v[68:69], v[68:69], v[14:15] op_sel_hi:[1,0] neg_lo:[0,1] neg_hi:[0,1]
	v_pk_add_f32 v[70:71], v[70:71], v[14:15] op_sel_hi:[1,0] neg_lo:[0,1] neg_hi:[0,1]
	v_pk_add_f32 v[72:73], v[72:73], v[14:15] op_sel_hi:[1,0] neg_lo:[0,1] neg_hi:[0,1]
	v_pk_add_f32 v[74:75], v[74:75], v[14:15] op_sel_hi:[1,0] neg_lo:[0,1] neg_hi:[0,1]
	v_pk_add_f32 v[76:77], v[76:77], v[14:15] op_sel_hi:[1,0] neg_lo:[0,1] neg_hi:[0,1]
	v_pk_add_f32 v[78:79], v[78:79], v[14:15] op_sel_hi:[1,0] neg_lo:[0,1] neg_hi:[0,1]
	v_pk_add_f32 v[48:49], v[48:49], v[14:15] op_sel_hi:[1,0] neg_lo:[0,1] neg_hi:[0,1]
	v_pk_add_f32 v[50:51], v[50:51], v[14:15] op_sel_hi:[1,0] neg_lo:[0,1] neg_hi:[0,1]
	v_pk_add_f32 v[52:53], v[52:53], v[14:15] op_sel_hi:[1,0] neg_lo:[0,1] neg_hi:[0,1]
	v_pk_add_f32 v[54:55], v[54:55], v[14:15] op_sel_hi:[1,0] neg_lo:[0,1] neg_hi:[0,1]
	v_pk_add_f32 v[56:57], v[56:57], v[14:15] op_sel_hi:[1,0] neg_lo:[0,1] neg_hi:[0,1]
	v_pk_add_f32 v[58:59], v[58:59], v[14:15] op_sel_hi:[1,0] neg_lo:[0,1] neg_hi:[0,1]
	v_pk_add_f32 v[60:61], v[60:61], v[14:15] op_sel_hi:[1,0] neg_lo:[0,1] neg_hi:[0,1]
	v_pk_add_f32 v[62:63], v[62:63], v[14:15] op_sel_hi:[1,0] neg_lo:[0,1] neg_hi:[0,1]
	v_pk_mul_f32 v[46:47], v[46:47], v[204:205] op_sel_hi:[1,0]
	v_pk_mul_f32 v[44:45], v[44:45], v[204:205] op_sel_hi:[1,0]
	v_pk_mul_f32 v[42:43], v[42:43], v[204:205] op_sel_hi:[1,0]
	v_pk_mul_f32 v[40:41], v[40:41], v[204:205] op_sel_hi:[1,0]
	v_pk_mul_f32 v[38:39], v[38:39], v[204:205] op_sel_hi:[1,0]
	v_pk_mul_f32 v[36:37], v[36:37], v[204:205] op_sel_hi:[1,0]
	v_pk_mul_f32 v[34:35], v[34:35], v[204:205] op_sel_hi:[1,0]
	v_pk_mul_f32 v[32:33], v[32:33], v[204:205] op_sel_hi:[1,0]
	v_pk_mul_f32 v[30:31], v[30:31], v[204:205] op_sel_hi:[1,0]
	v_pk_mul_f32 v[28:29], v[28:29], v[204:205] op_sel_hi:[1,0]
	v_pk_mul_f32 v[26:27], v[26:27], v[204:205] op_sel_hi:[1,0]
	v_pk_mul_f32 v[24:25], v[24:25], v[204:205] op_sel_hi:[1,0]
	v_pk_mul_f32 v[22:23], v[22:23], v[204:205] op_sel_hi:[1,0]
	v_pk_mul_f32 v[20:21], v[20:21], v[204:205] op_sel_hi:[1,0]
	v_pk_mul_f32 v[18:19], v[18:19], v[204:205] op_sel_hi:[1,0]
	v_pk_mul_f32 v[16:17], v[16:17], v[204:205] op_sel_hi:[1,0]
.LBB0_2132:
	v_exp_f32_e32 v14, v64
	v_exp_f32_e32 v64, v65
	v_exp_f32_e32 v65, v66
	v_exp_f32_e32 v66, v67
	v_add_f32_e32 v15, 0, v14
	v_exp_f32_e32 v67, v68
	v_add_f32_e32 v15, v64, v15
	v_exp_f32_e32 v68, v69
	v_add_f32_e32 v15, v65, v15
	v_exp_f32_e32 v69, v70
	v_add_f32_e32 v15, v66, v15
	v_exp_f32_e32 v70, v71
	v_add_f32_e32 v15, v67, v15
	v_exp_f32_e32 v71, v72
	v_add_f32_e32 v15, v68, v15
	v_exp_f32_e32 v72, v73
	v_add_f32_e32 v15, v69, v15
	v_exp_f32_e32 v73, v74
	v_add_f32_e32 v15, v70, v15
	v_exp_f32_e32 v74, v75
	v_exp_f32_e32 v75, v76
	v_exp_f32_e32 v76, v77
	v_exp_f32_e32 v77, v78
	v_exp_f32_e32 v78, v79
	v_exp_f32_e32 v79, v48
	v_exp_f32_e32 v203, v49
	v_exp_f32_e32 v204, v50
	v_exp_f32_e32 v205, v51
	v_cvt_pk_bf16_f32 v48, v14, v64
	v_cvt_pk_bf16_f32 v49, v65, v66
	v_cvt_pk_bf16_f32 v50, v67, v68
	v_cvt_pk_bf16_f32 v51, v69, v70
	v_add_f32_e32 v15, v71, v15
	v_add_f32_e32 v15, v72, v15
	s_waitcnt lgkmcnt(7)
	v_mfma_f32_32x32x16_bf16 v[32:47], v[160:163], v[48:51], v[32:47]
	v_add_f32_e32 v15, v73, v15
	v_add_f32_e32 v15, v74, v15
	v_add_f32_e32 v15, v75, v15
	v_add_f32_e32 v15, v76, v15
	v_add_f32_e32 v15, v77, v15
	v_add_f32_e32 v15, v78, v15
	v_exp_f32_e32 v206, v52
	s_waitcnt lgkmcnt(3)
	v_mfma_f32_32x32x16_bf16 v[16:31], v[156:159], v[48:51], v[16:31]
	v_exp_f32_e32 v207, v53
	v_exp_f32_e32 v208, v54
	v_exp_f32_e32 v209, v55
	v_cvt_pk_bf16_f32 v52, v71, v72
	v_cvt_pk_bf16_f32 v53, v73, v74
	v_cvt_pk_bf16_f32 v54, v75, v76
	v_cvt_pk_bf16_f32 v55, v77, v78
	v_add_f32_e32 v15, v79, v15
	v_add_f32_e32 v15, v203, v15
	v_mfma_f32_32x32x16_bf16 v[32:47], v[152:155], v[52:55], v[32:47]
	v_add_f32_e32 v15, v204, v15
	v_add_f32_e32 v15, v205, v15
	v_add_f32_e32 v15, v206, v15
	v_exp_f32_e32 v210, v56
	v_add_f32_e32 v15, v207, v15
	v_exp_f32_e32 v211, v57
	v_add_f32_e32 v15, v208, v15
	s_waitcnt lgkmcnt(2)
	v_mfma_f32_32x32x16_bf16 v[16:31], v[148:151], v[52:55], v[16:31]
	v_exp_f32_e32 v212, v58
	v_add_f32_e32 v15, v209, v15
	v_exp_f32_e32 v213, v59
	v_cvt_pk_bf16_f32 v56, v79, v203
	v_cvt_pk_bf16_f32 v57, v204, v205
	v_cvt_pk_bf16_f32 v58, v206, v207
	v_cvt_pk_bf16_f32 v59, v208, v209
	v_add_f32_e32 v15, v210, v15
	v_exp_f32_e32 v214, v60
	v_mfma_f32_32x32x16_bf16 v[32:47], v[144:147], v[56:59], v[32:47]
	v_add_f32_e32 v15, v211, v15
	v_exp_f32_e32 v215, v61
	v_add_f32_e32 v15, v212, v15
	v_exp_f32_e32 v216, v62
	v_add_f32_e32 v15, v213, v15
	v_exp_f32_e32 v63, v63
	v_add_f32_e32 v15, v214, v15
	s_waitcnt lgkmcnt(1)
	v_mfma_f32_32x32x16_bf16 v[16:31], v[10:13], v[56:59], v[16:31]
	v_add_f32_e32 v15, v215, v15
	v_add_f32_e32 v15, v216, v15
	v_add_f32_e32 v15, v63, v15
	v_cvt_pk_bf16_f32 v60, v210, v211
	v_cvt_pk_bf16_f32 v61, v212, v213
	v_cvt_pk_bf16_f32 v62, v214, v215
	v_cvt_pk_bf16_f32 v63, v216, v63
	v_add_f32_e32 v175, v175, v15
	s_andn2_b64 s[10:11], s[10:11], exec
	v_mfma_f32_32x32x16_bf16 v[32:47], v[6:9], v[60:63], v[32:47]
	s_waitcnt lgkmcnt(0)
	v_mfma_f32_32x32x16_bf16 v[16:31], v[2:5], v[60:63], v[16:31]
	s_branch .LBB0_2133
.Lmy_ia0_b:
	s_or_b64 exec, exec, s[14:15]
	s_cmp_gt_i32 s18, s16
	s_cbranch_scc1 .Lmy_w7_nl
	v_add_u32_e32 v226, 0x8e00, v182
	s_waitcnt vmcnt(9)
	ds_write_b128 v200, v[120:123] offset:23040
	s_waitcnt vmcnt(8)
	ds_write_b128 v201, v[124:127] offset:23040
	s_waitcnt vmcnt(7)
	ds_write_b128 v202, v[132:135] offset:23040
	s_waitcnt vmcnt(6)
	ds_write2_b64 v226, v[136:137], v[138:139] offset1:1
	v_add_u32_e32 v226, 0x8e00, v184
	s_waitcnt vmcnt(5)
	ds_write2_b64 v226, v[140:141], v[142:143] offset1:1
	s_branch .Lmy_w7_dn

; template <int DQK, int MODE> ...
;     ...
;   auto step = [&](TRegs& R, int it) -> bool {
;     const int j = jstart + dir * it;
;     const int st = it & 1;
;     lstore(R, st);
;     if (MODE == 2) {
;       int alive = (carry != 0.f) ? 1 : 0;
;       if (!__syncthreads_or(alive)) return false;
;     } else {
;       __syncthreads();
;     }
;     if (it + 2 < ntile) gload(R, j + 2 * dir);
;     __builtin_amdgcn_sched_barrier(0);
;     if (active && j <= hiw && j >= low) {
;       const u16* Ks = lds + st * STG;
;       const u16* Vs = Ks + KT;
;       f32x16 S[2];
;       const bool far = (MODE == 1) && ((qpos0 + 32 * w) - (j * 64 + 63) >= 256);
;       const float cinit = (MODE != 2) ? (-m_run + (far ? btab[512] : 0.f)) : 0.f;
;       {
;         bf16x8 kf[2][NKK];
; #pragma unroll
;         for (int ku = 0; ku < 2; ++ku)
; #pragma unroll
;           for (int kk = 0; kk < NKK; ++kk)
;             kf[ku][kk] = *(const bf16x8*)(Ks + (ku * 32 + ql) * KST + kk * 16 + hh * 8);
;         __builtin_amdgcn_sched_barrier(0);
; #pragma unroll
;         for (int ku = 0; ku < 2; ++ku)
; #pragma unroll
;           for (int r = 0; r < 16; ++r) S[ku][r] = cinit;
; #pragma unroll
;         for (int kk = 0; kk < NKK; ++kk)
; #pragma unroll
;           for (int ku = 0; ku < 2; ++ku)
;             S[ku] = __builtin_amdgcn_mfma_f32_32x32x16_bf16(kf[ku][kk], qf[kk], S[ku], 0, 0, 0);
;       }
.Lmy_w7_dn:
.LBB0_2133:
	s_or_b64 exec, exec, s[14:15]
	s_add_i32 s14, s17, -3
	s_cmp_ge_i32 s14, s16
	s_cbranch_scc1 .LBB0_2126
	v_add_u32_e32 v220, s9, v169
	v_add_u32_e32 v220, 0xfc0000c0, v220
	v_add_u32_e32 v222, s9, v171
	v_mad_i64_i32 v[220:221], s[14:15], v220, s87, v[176:177]
	v_add_u32_e32 v222, 0xfc0000c0, v222
	v_mad_i64_i32 v[222:223], s[14:15], v222, s87, v[178:179]
	v_add_u32_e32 v224, s9, v173
	v_add_u32_e32 v224, 0xfc0000c0, v224
	v_mad_i64_i32 v[224:225], s[14:15], v224, s87, v[180:181]
	v_lshl_add_u64 v[244:245], v[186:187], 0, s[2:3]
	v_add_co_u32_e32 v244, vcc, 0x6000, v244
	s_nop 1
	v_addc_co_u32_e32 v245, vcc, -2, v245, vcc
	v_lshl_add_u64 v[248:249], v[188:189], 0, s[2:3]
	v_add_co_u32_e32 v248, vcc, 0x6000, v248
	s_nop 1
	v_addc_co_u32_e32 v249, vcc, -2, v249, vcc
	s_cmp_gt_i32 s17, s16
	s_waitcnt lgkmcnt(0)
	s_barrier
	s_cbranch_scc1 .LBB0_2136
	global_load_dwordx4 v[120:123], v[220:221], off
	global_load_dwordx4 v[124:127], v[222:223], off
	global_load_dwordx4 v[132:135], v[224:225], off
	global_load_dwordx4 v[136:139], v[244:245], off
	global_load_dwordx4 v[140:143], v[248:249], off
.LBB0_2136:
	s_add_i32 s21, s21, 0xffeffffe
	v_cmp_le_i32_e32 vcc, s21, v197
	s_and_b64 s[14:15], s[12:13], vcc
	v_cmp_ge_u32_e32 vcc, s21, v199
	s_and_b64 s[30:31], s[14:15], vcc
	s_and_saveexec_b64 s[14:15], s[30:31]
	s_cbranch_execz .Lmy_ia1_b
	ds_read_b128 v[2:5], v183 offset:23040
	ds_read_b128 v[6:9], v183 offset:23072
	ds_read_b128 v[10:13], v183 offset:23104
	ds_read_b128 v[144:147], v183 offset:23136
	ds_read_b128 v[148:151], v183 offset:23168
	ds_read_b128 v[152:155], v183 offset:23200
	ds_read_b128 v[156:159], v183 offset:29696
	ds_read_b128 v[160:163], v183 offset:29728
	ds_read_b128 v[204:207], v183 offset:29760
	ds_read_b128 v[208:211], v183 offset:29792
	ds_read_b128 v[212:215], v183 offset:29824
	ds_read_b128 v[216:219], v183 offset:29856
	s_waitcnt lgkmcnt(11)
	v_mfma_f32_32x32x16_bf16 v[64:79], v[2:5], v[84:87], v[228:243]
	v_add_u32_e32 v2, 0x8800, v185
	s_waitcnt lgkmcnt(5)
	v_mfma_f32_32x32x16_bf16 v[48:63], v[156:159], v[84:87], v[228:243]
	s_cmp_gt_i32 s17, s16
	s_cbranch_scc1 .Lmy_w6_nl
	v_add_u32_e32 v226, 0x3400, v182
	s_waitcnt vmcnt(9)
	ds_write_b128 v200, v[104:107]
	s_waitcnt vmcnt(8)
	ds_write_b128 v201, v[108:111]
	s_waitcnt vmcnt(7)
	ds_write_b128 v202, v[112:115]
	s_waitcnt vmcnt(6)
	ds_write2_b64 v226, v[116:117], v[118:119] offset1:1
	v_add_u32_e32 v226, 0x3400, v184
	s_waitcnt vmcnt(5)
	ds_write2_b64 v226, v[128:129], v[130:131] offset1:1
	s_branch .Lmy_w6_dn
.Lmy_w6_nl:
	v_add_u32_e32 v226, 0x3400, v182
	s_waitcnt vmcnt(4)
	ds_write_b128 v200, v[104:107]
	s_waitcnt vmcnt(3)
	ds_write_b128 v201, v[108:111]
	s_waitcnt vmcnt(2)
	ds_write_b128 v202, v[112:115]
	s_waitcnt vmcnt(1)
	ds_write2_b64 v226, v[116:117], v[118:119] offset1:1
	v_add_u32_e32 v226, 0x3400, v184
	s_waitcnt vmcnt(0)
	ds_write2_b64 v226, v[128:129], v[130:131] offset1:1
; template <int DQK, int MODE> ...
;     ...
;         for (int kk = 0; kk < NKK; ++kk)
; #pragma unroll
;           for (int ku = 0; ku < 2; ++ku)
;             S[ku] = __builtin_amdgcn_mfma_f32_32x32x16_bf16(kf[ku][kk], qf[kk], S[ku], 0, 0, 0);
;       }
;       u32x4 vf[2][4];
;       if (MODE != 2) {
; #pragma unroll
;         for (int du = 0; du < 2; ++du)
; #pragma unroll
;           for (int s4 = 0; s4 < 4; ++s4) {
;             const u16* vp = Vs + (du * 32 + ql) * VST + 16 * s4 + 4 * hh;
;             u32x2 a = *(const u32x2*)vp;
;             u32x2 b = *(const u32x2*)(vp + 8);
;             vf[du][s4] = (u32x4){a.x, a.y, b.x, b.y};
;           }
;         __builtin_amdgcn_sched_barrier(0);
;       }
;       bf16x8 pf[4];
;       if (MODE != 2) {
;         if (MODE == 1 && !far) {
;           const bool noclip = ((qpos0 + 32 * w + 31) - j * 64 <= 256) && ((qpos0 + 32 * w) - (j * 64 + 63) >= -256);
;           if (noclip) {
;             const float* bt = btab + 256 + qpos - j * 64;
; #pragma unroll
;             for (int ku = 0; ku < 2; ++ku)
; #pragma unroll
;               for (int r = 0; r < 16; ++r) S[ku][r] += bt[-(32 * ku + (r & 3) + 8 * (r >> 2) + 4 * hh)];
;           } else {
; #pragma unroll
;             for (int ku = 0; ku < 2; ++ku)
; #pragma unroll
;               for (int r = 0; r < 16; ++r) {
;                 int key = 32 * ku + (r & 3) + 8 * (r >> 2) + 4 * hh;
;                 int rel = qpos - (j * 64 + key);
;                 rel = min(256, max(-256, rel)) + 256;
;                 S[ku][r] += btab[rel];
;               }
;           }
;         }
;         float mx = -1e30f;
; #pragma unroll
;         for (int ku = 0; ku < 2; ++ku)
; #pragma unroll
;           for (int r = 0; r < 16; ++r) mx = fmaxf(mx, S[ku][r]);
;         if (__builtin_amdgcn_ballot_w64(first || mx > 6.f) != 0ull) {
;           mx = xhalf_max(mx);
;           const float d = first ? mx : (mx > 6.f ? mx : 0.f);
;           const float alpha = first ? 1.f : __builtin_amdgcn_exp2f(-d);
;           m_run += d;
;           lsum *= alpha;
; #pragma unroll
;           for (int ku = 0; ku < 2; ++ku)
; #pragma unroll
;             for (int r = 0; r < 16; ++r) S[ku][r] -= d;
; #pragma unroll
;           for (int du = 0; du < 2; ++du)
; #pragma unroll
;             for (int r = 0; r < 16; ++r) O[du][r] *= alpha;
;         }
.Lmy_w6_dn:
	v_mfma_f32_32x32x16_bf16 v[64:79], v[6:9], v[80:83], v[64:79]
	s_waitcnt lgkmcnt(9)
	v_mfma_f32_32x32x16_bf16 v[48:63], v[160:163], v[80:83], v[48:63]
	ds_read2_b64 v[160:163], v2 offset0:192 offset1:194
	v_mfma_f32_32x32x16_bf16 v[64:79], v[10:13], v[92:95], v[64:79]
	s_waitcnt lgkmcnt(9)
	v_mfma_f32_32x32x16_bf16 v[48:63], v[204:207], v[92:95], v[48:63]
	v_mfma_f32_32x32x16_bf16 v[64:79], v[144:147], v[88:91], v[64:79]
	s_waitcnt lgkmcnt(8)
	v_mfma_f32_32x32x16_bf16 v[48:63], v[208:211], v[88:91], v[48:63]
	v_mfma_f32_32x32x16_bf16 v[64:79], v[148:151], v[100:103], v[64:79]
	s_waitcnt lgkmcnt(7)
	v_mfma_f32_32x32x16_bf16 v[48:63], v[212:215], v[100:103], v[48:63]
	v_mfma_f32_32x32x16_bf16 v[64:79], v[152:155], v[96:99], v[64:79]
	ds_read2_b64 v[152:155], v2 offset0:196 offset1:198
	ds_read2_b64 v[144:147], v2 offset0:200 offset1:202
	ds_read2_b64 v[6:9], v2 offset0:204 offset1:206
	v_add_u32_e32 v2, 0xa000, v185
	ds_read2_b64 v[156:159], v2 offset0:32 offset1:34
	ds_read2_b64 v[148:151], v2 offset0:36 offset1:38
	ds_read2_b64 v[10:13], v2 offset0:40 offset1:42
	ds_read2_b64 v[2:5], v2 offset0:44 offset1:46
	s_waitcnt lgkmcnt(13)
	v_mfma_f32_32x32x16_bf16 v[48:63], v[216:219], v[96:99], v[48:63]
	s_nop 1
	v_max3_f32 v14, v64, s96, v65
	v_max3_f32 v14, v14, v66, v67
	v_max3_f32 v14, v14, v68, v69
	v_max3_f32 v14, v14, v70, v71
	v_max3_f32 v14, v14, v72, v73
	v_max3_f32 v14, v14, v74, v75
	v_max3_f32 v14, v14, v76, v77
	v_max3_f32 v14, v14, v78, v79
	s_nop 1
	v_max3_f32 v14, v14, v48, v49
	v_max3_f32 v14, v14, v50, v51
	v_max3_f32 v14, v14, v52, v53
	v_max3_f32 v14, v14, v54, v55
	v_max3_f32 v14, v14, v56, v57
	v_max3_f32 v14, v14, v58, v59
	v_max3_f32 v14, v14, v60, v61
	v_max3_f32 v14, v14, v62, v63
	v_cmp_lt_f32_e32 vcc, s97, v14
	s_or_b64 vcc, s[10:11], vcc
	s_cbranch_vccz .LBB0_2124
	v_mov_b32_e32 v15, v14
	s_nop 1
	v_permlane32_swap_b32_e32 v14, v15
	v_max_f32_e32 v15, v15, v15
	v_max_f32_e32 v14, v14, v14
	v_max_f32_e32 v14, v14, v15
	v_cmp_lt_f32_e32 vcc, s97, v14
	s_or_b64 vcc, s[10:11], vcc
	s_nop 0
	v_cndmask_b32_e32 v14, 0, v14, vcc
	v_exp_f32_e64 v15, -v14
	v_add_f32_e32 v0, v0, v14
	v_sub_f32_e32 v228, 0, v0
	v_mov_b32_e32 v229, v228
	v_mov_b32_e32 v230, v228
	v_mov_b32_e32 v231, v228
	v_mov_b32_e32 v232, v228
	v_mov_b32_e32 v233, v228
	v_mov_b32_e32 v234, v228
	v_mov_b32_e32 v235, v228
	v_mov_b32_e32 v236, v228
	v_mov_b32_e32 v237, v228
	v_mov_b32_e32 v238, v228
	v_mov_b32_e32 v239, v228
	v_mov_b32_e32 v240, v228
	v_mov_b32_e32 v241, v228
	v_mov_b32_e32 v242, v228
	v_mov_b32_e32 v243, v228
	v_cndmask_b32_e64 v204, v15, 1.0, s[10:11]
	v_mul_f32_e32 v175, v175, v204
	v_pk_add_f32 v[64:65], v[64:65], v[14:15] op_sel_hi:[1,0] neg_lo:[0,1] neg_hi:[0,1]
	v_pk_add_f32 v[66:67], v[66:67], v[14:15] op_sel_hi:[1,0] neg_lo:[0,1] neg_hi:[0,1]
	v_pk_add_f32 v[68:69], v[68:69], v[14:15] op_sel_hi:[1,0] neg_lo:[0,1] neg_hi:[0,1]
	v_pk_add_f32 v[70:71], v[70:71], v[14:15] op_sel_hi:[1,0] neg_lo:[0,1] neg_hi:[0,1]
	v_pk_add_f32 v[72:73], v[72:73], v[14:15] op_sel_hi:[1,0] neg_lo:[0,1] neg_hi:[0,1]
	v_pk_add_f32 v[74:75], v[74:75], v[14:15] op_sel_hi:[1,0] neg_lo:[0,1] neg_hi:[0,1]
	v_pk_add_f32 v[76:77], v[76:77], v[14:15] op_sel_hi:[1,0] neg_lo:[0,1] neg_hi:[0,1]
	v_pk_add_f32 v[78:79], v[78:79], v[14:15] op_sel_hi:[1,0] neg_lo:[0,1] neg_hi:[0,1]
	v_pk_add_f32 v[48:49], v[48:49], v[14:15] op_sel_hi:[1,0] neg_lo:[0,1] neg_hi:[0,1]
	v_pk_add_f32 v[50:51], v[50:51], v[14:15] op_sel_hi:[1,0] neg_lo:[0,1] neg_hi:[0,1]
	v_pk_add_f32 v[52:53], v[52:53], v[14:15] op_sel_hi:[1,0] neg_lo:[0,1] neg_hi:[0,1]
	v_pk_add_f32 v[54:55], v[54:55], v[14:15] op_sel_hi:[1,0] neg_lo:[0,1] neg_hi:[0,1]
	v_pk_add_f32 v[56:57], v[56:57], v[14:15] op_sel_hi:[1,0] neg_lo:[0,1] neg_hi:[0,1]
	v_pk_add_f32 v[58:59], v[58:59], v[14:15] op_sel_hi:[1,0] neg_lo:[0,1] neg_hi:[0,1]
	v_pk_add_f32 v[60:61], v[60:61], v[14:15] op_sel_hi:[1,0] neg_lo:[0,1] neg_hi:[0,1]
	v_pk_add_f32 v[62:63], v[62:63], v[14:15] op_sel_hi:[1,0] neg_lo:[0,1] neg_hi:[0,1]
	v_pk_mul_f32 v[46:47], v[46:47], v[204:205] op_sel_hi:[1,0]
	v_pk_mul_f32 v[44:45], v[44:45], v[204:205] op_sel_hi:[1,0]
	v_pk_mul_f32 v[42:43], v[42:43], v[204:205] op_sel_hi:[1,0]
	v_pk_mul_f32 v[40:41], v[40:41], v[204:205] op_sel_hi:[1,0]
	v_pk_mul_f32 v[38:39], v[38:39], v[204:205] op_sel_hi:[1,0]
	v_pk_mul_f32 v[36:37], v[36:37], v[204:205] op_sel_hi:[1,0]
	v_pk_mul_f32 v[34:35], v[34:35], v[204:205] op_sel_hi:[1,0]
	v_pk_mul_f32 v[32:33], v[32:33], v[204:205] op_sel_hi:[1,0]
	v_pk_mul_f32 v[30:31], v[30:31], v[204:205] op_sel_hi:[1,0]
	v_pk_mul_f32 v[28:29], v[28:29], v[204:205] op_sel_hi:[1,0]
	v_pk_mul_f32 v[26:27], v[26:27], v[204:205] op_sel_hi:[1,0]
	v_pk_mul_f32 v[24:25], v[24:25], v[204:205] op_sel_hi:[1,0]
	v_pk_mul_f32 v[22:23], v[22:23], v[204:205] op_sel_hi:[1,0]
	v_pk_mul_f32 v[20:21], v[20:21], v[204:205] op_sel_hi:[1,0]
	v_pk_mul_f32 v[18:19], v[18:19], v[204:205] op_sel_hi:[1,0]
	v_pk_mul_f32 v[16:17], v[16:17], v[204:205] op_sel_hi:[1,0]
	s_branch .LBB0_2124
.Lmy_ia1_b:
	s_or_b64 exec, exec, s[14:15]
	s_cmp_gt_i32 s17, s16
	s_cbranch_scc1 .Lmy_w8_nl
	v_add_u32_e32 v226, 0x3400, v182
	s_waitcnt vmcnt(9)
	ds_write_b128 v200, v[104:107]
	s_waitcnt vmcnt(8)
	ds_write_b128 v201, v[108:111]
	s_waitcnt vmcnt(7)
	ds_write_b128 v202, v[112:115]
	s_waitcnt vmcnt(6)
	ds_write2_b64 v226, v[116:117], v[118:119] offset1:1
	v_add_u32_e32 v226, 0x3400, v184
	s_waitcnt vmcnt(5)
	ds_write2_b64 v226, v[128:129], v[130:131] offset1:1
	s_branch .Lmy_w8_dn

; template <int DQK, int MODE> ...
;     ...
;   if (active) {
;     if (MODE != 2) {
;       float lt = lsum + __shfl_xor(lsum, 32);
;       float inv = 1.f / lt;
; #pragma unroll
;       for (int du = 0; du < 2; ++du)
; #pragma unroll
;         for (int r = 0; r < 16; ++r) O[du][r] *= inv;
;     }
;     float ss = 0.f;
; #pragma unroll
;     for (int du = 0; du < 2; ++du)
; #pragma unroll
;       for (int r = 0; r < 16; ++r) ss += O[du][r] * O[du][r];
;     ss += __shfl_xor(ss, 32);
;     const float rstd = rsqrtf(ss * (1.f / 64.f) + EPS);
;     const long m = (long)mrow0 + 32 * w + ql;
;     const float* og = p.out_g + l * 1024 + colbase;
;     const u16* gt = p.gates + m * 1024 + colbase;
;     u16* yo = p.xn + m * 1024 + colbase;
.LBB0_2139:
	s_waitcnt lgkmcnt(0)
	s_ashr_i32 s35, s34, 31
	s_and_saveexec_b64 s[2:3], s[0:1]
	s_xor_b64 s[0:1], exec, s[2:3]
	s_cbranch_execz .LBB0_2141
	v_and_b32_e32 v2, 64, v194
	v_xor_b32_e32 v0, 32, v194
	v_add_u32_e32 v2, 64, v2
	v_cmp_lt_i32_e32 vcc, v0, v2
	v_mov_b32_e32 v171, v1
	v_ashrrev_i32_e32 v173, 31, v172
	v_cndmask_b32_e32 v0, v194, v0, vcc
	v_lshlrev_b32_e32 v76, 2, v0
	ds_bpermute_b32 v0, v76, v175
	v_lshl_add_u64 v[2:3], v[170:171], 0, s[34:35]
	s_mov_b32 s45, s19
	v_lshl_add_u64 v[2:3], v[2:3], 0, v[172:173]
	v_readlane_b32 s8, v253, 38
	s_waitcnt lgkmcnt(0)
	v_add_f32_e32 v0, v175, v0
	v_div_scale_f32 v4, s[2:3], v0, v0, 1.0
	s_lshl_b64 s[2:3], s[44:45], 2
	s_add_u32 s2, s26, s2
	v_lshlrev_b64 v[14:15], 11, v[2:3]
	v_readlane_b32 s9, v253, 39
	v_readlane_b32 s12, v253, 42
	v_readlane_b32 s13, v253, 43
	s_addc_u32 s3, s33, s3
	s_lshl_b64 s[8:9], s[44:45], 1
	v_lshl_add_u64 v[2:3], s[12:13], 0, v[14:15]
	v_lshl_add_u64 v[2:3], v[2:3], 0, s[8:9]
	v_mov_b32_e32 v175, v1
	v_lshl_add_u64 v[2:3], v[2:3], 0, v[174:175]
	global_load_dwordx2 v[48:49], v[2:3], off
	global_load_dwordx4 v[10:13], v168, s[2:3]
	v_rcp_f32_e32 v5, v4
	v_lshl_add_u64 v[14:15], s[60:61], 0, v[14:15]
	v_lshl_add_u64 v[14:15], v[14:15], 0, s[8:9]
	s_mov_b32 s8, 0x800000
	v_fma_f32 v6, -v4, v5, 1.0
	v_fmac_f32_e32 v5, v6, v5
	v_div_scale_f32 v6, vcc, 1.0, v0, 1.0
	v_mul_f32_e32 v7, v6, v5
	v_fma_f32 v8, -v4, v7, v6
	v_fmac_f32_e32 v7, v8, v5
	v_fma_f32 v4, -v4, v7, v6
	v_div_fmas_f32 v4, v4, v5, v7
	v_div_fixup_f32 v0, v4, v0, 1.0
	v_pk_mul_f32 v[32:33], v[32:33], v[0:1] op_sel_hi:[1,0]
	v_pk_mul_f32 v[34:35], v[34:35], v[0:1] op_sel_hi:[1,0]
	v_pk_mul_f32 v[52:53], v[32:33], v[32:33]
	v_pk_mul_f32 v[8:9], v[26:27], v[0:1] op_sel_hi:[1,0]
	v_pk_mul_f32 v[6:7], v[28:29], v[0:1] op_sel_hi:[1,0]
	v_pk_mul_f32 v[4:5], v[30:31], v[0:1] op_sel_hi:[1,0]
	v_pk_mul_f32 v[50:51], v[34:35], v[34:35]
	v_pk_mul_f32 v[38:39], v[38:39], v[0:1] op_sel_hi:[1,0]
	v_pk_mul_f32 v[36:37], v[36:37], v[0:1] op_sel_hi:[1,0]
	v_pk_mul_f32 v[42:43], v[42:43], v[0:1] op_sel_hi:[1,0]
	v_pk_mul_f32 v[40:41], v[40:41], v[0:1] op_sel_hi:[1,0]
	v_pk_mul_f32 v[46:47], v[46:47], v[0:1] op_sel_hi:[1,0]
	v_pk_mul_f32 v[44:45], v[44:45], v[0:1] op_sel_hi:[1,0]
	v_pk_mul_f32 v[18:19], v[18:19], v[0:1] op_sel_hi:[1,0]
	v_pk_mul_f32 v[16:17], v[16:17], v[0:1] op_sel_hi:[1,0]
	v_pk_mul_f32 v[22:23], v[22:23], v[0:1] op_sel_hi:[1,0]
	v_pk_mul_f32 v[20:21], v[20:21], v[0:1] op_sel_hi:[1,0]
	v_pk_mul_f32 v[24:25], v[24:25], v[0:1] op_sel_hi:[1,0]
	v_add_f32_e32 v0, v52, v53
	v_add_f32_e32 v0, v50, v0
	v_pk_mul_f32 v[56:57], v[36:37], v[36:37]
	v_add_f32_e32 v0, v51, v0
	v_add_f32_e32 v0, v56, v0
	v_pk_mul_f32 v[54:55], v[38:39], v[38:39]
	v_add_f32_e32 v0, v57, v0
	v_add_f32_e32 v0, v54, v0
	v_pk_mul_f32 v[60:61], v[40:41], v[40:41]
	v_add_f32_e32 v0, v55, v0
	v_add_f32_e32 v0, v60, v0
	v_pk_mul_f32 v[58:59], v[42:43], v[42:43]
	v_add_f32_e32 v0, v61, v0
	v_add_f32_e32 v0, v58, v0
	v_pk_mul_f32 v[64:65], v[44:45], v[44:45]
	v_add_f32_e32 v0, v59, v0
	v_add_f32_e32 v0, v64, v0
	v_pk_mul_f32 v[62:63], v[46:47], v[46:47]
	v_add_f32_e32 v0, v65, v0
	v_add_f32_e32 v0, v62, v0
	v_pk_mul_f32 v[68:69], v[16:17], v[16:17]
	v_add_f32_e32 v0, v63, v0
	v_add_f32_e32 v0, v68, v0
	v_pk_mul_f32 v[66:67], v[18:19], v[18:19]
	v_add_f32_e32 v0, v69, v0
	v_add_f32_e32 v0, v66, v0
	v_pk_mul_f32 v[72:73], v[20:21], v[20:21]
	v_add_f32_e32 v0, v67, v0
	v_add_f32_e32 v0, v72, v0
	v_pk_mul_f32 v[70:71], v[22:23], v[22:23]
	v_add_f32_e32 v0, v73, v0
	v_add_f32_e32 v0, v70, v0
	v_pk_mul_f32 v[74:75], v[24:25], v[24:25]
	v_add_f32_e32 v0, v71, v0
	v_add_f32_e32 v0, v74, v0
	v_pk_mul_f32 v[26:27], v[8:9], v[8:9]
	v_add_f32_e32 v0, v75, v0
	v_add_f32_e32 v0, v26, v0
	v_pk_mul_f32 v[28:29], v[6:7], v[6:7]
	v_add_f32_e32 v0, v27, v0
	v_add_f32_e32 v0, v28, v0
	v_pk_mul_f32 v[30:31], v[4:5], v[4:5]
	v_add_f32_e32 v0, v29, v0
	v_add_f32_e32 v0, v30, v0
	v_add_f32_e32 v0, v31, v0
	ds_bpermute_b32 v28, v76, v0
	s_waitcnt vmcnt(1)
	v_and_b32_e32 v29, 0xffff0000, v48
	v_lshlrev_b32_e32 v26, 16, v49
	v_and_b32_e32 v27, 0xffff0000, v49
	v_lshl_add_u64 v[14:15], v[14:15], 0, v[174:175]
	s_waitcnt lgkmcnt(0)
	v_add_f32_e32 v0, v0, v28
	v_fmamk_f32 v0, v0, 0x3c800000, v192
	v_mul_f32_e32 v28, 0x4b800000, v0
	v_cmp_gt_f32_e32 vcc, s8, v0
	v_readlane_b32 s10, v253, 40
	v_readlane_b32 s11, v253, 41
	v_cndmask_b32_e32 v0, v0, v28, vcc
	v_rsq_f32_e32 v0, v0
	v_lshlrev_b32_e32 v28, 16, v48
	v_readlane_b32 s14, v253, 44
	v_readlane_b32 s15, v253, 45
	v_mul_f32_e32 v30, 0x45800000, v0
	v_cndmask_b32_e32 v0, v0, v30, vcc
	v_pk_mul_f32 v[30:31], v[32:33], v[0:1] op_sel_hi:[1,0]
	v_pk_mul_f32 v[16:17], v[16:17], v[0:1] op_sel_hi:[1,0]
	s_waitcnt vmcnt(0)
; template <int DQK, int MODE> ...
;     ...
; #pragma unroll
;     for (int du = 0; du < 2; ++du)
; #pragma unroll
;       for (int c = 0; c < 4; ++c) {
;         const int d0 = 32 * du + 8 * c + 4 * hh;
;         u32x2 g2 = *(const u32x2*)(gt + d0);
;         f32x4 o4 = *(const f32x4*)(og + d0);
;         float y0 = O[du][4 * c + 0] * rstd * o4.x * __uint_as_float(g2.x << 16);
;         float y1 = O[du][4 * c + 1] * rstd * o4.y * __uint_as_float(g2.x & 0xffff0000u);
;         float y2 = O[du][4 * c + 2] * rstd * o4.z * __uint_as_float(g2.y << 16);
;         float y3 = O[du][4 * c + 3] * rstd * o4.w * __uint_as_float(g2.y & 0xffff0000u);
;         u32x2 o = {pack2(y0, y1), pack2(y2, y3)};
;         *(u32x2*)(yo + d0) = o;
;       }
	v_pk_mul_f32 v[10:11], v[10:11], v[30:31]
	v_pk_mul_f32 v[30:31], v[38:39], v[0:1] op_sel_hi:[1,0]
	v_pk_mul_f32 v[10:11], v[10:11], v[28:29]
	v_pk_mul_f32 v[28:29], v[34:35], v[0:1] op_sel_hi:[1,0]
	v_cvt_pk_bf16_f32 v10, v10, v11
	v_pk_mul_f32 v[12:13], v[12:13], v[28:29]
	v_pk_mul_f32 v[28:29], v[36:37], v[0:1] op_sel_hi:[1,0]
	v_pk_mul_f32 v[12:13], v[12:13], v[26:27]
	v_pk_mul_f32 v[18:19], v[18:19], v[0:1] op_sel_hi:[1,0]
	v_cvt_pk_bf16_f32 v11, v12, v13
	global_store_dwordx2 v[14:15], v[10:11], off
	global_load_dwordx4 v[10:13], v168, s[2:3] offset:32
	s_nop 0
	global_load_dwordx2 v[26:27], v[2:3], off offset:16
	v_pk_mul_f32 v[8:9], v[8:9], v[0:1] op_sel_hi:[1,0]
	v_pk_mul_f32 v[6:7], v[6:7], v[0:1] op_sel_hi:[1,0]
	v_pk_mul_f32 v[4:5], v[4:5], v[0:1] op_sel_hi:[1,0]
	s_waitcnt vmcnt(1)
	v_pk_mul_f32 v[10:11], v[10:11], v[28:29]
	s_waitcnt vmcnt(0)
	v_lshlrev_b32_e32 v28, 16, v26
	v_and_b32_e32 v29, 0xffff0000, v26
	v_pk_mul_f32 v[12:13], v[12:13], v[30:31]
	v_lshlrev_b32_e32 v26, 16, v27
	v_and_b32_e32 v27, 0xffff0000, v27
	v_pk_mul_f32 v[10:11], v[10:11], v[28:29]
	v_pk_mul_f32 v[12:13], v[12:13], v[26:27]
	v_cvt_pk_bf16_f32 v10, v10, v11
	v_cvt_pk_bf16_f32 v11, v12, v13
	global_store_dwordx2 v[14:15], v[10:11], off offset:16
	global_load_dwordx4 v[10:13], v168, s[2:3] offset:64
	s_nop 0
	global_load_dwordx2 v[26:27], v[2:3], off offset:32
	v_pk_mul_f32 v[28:29], v[40:41], v[0:1] op_sel_hi:[1,0]
	v_pk_mul_f32 v[30:31], v[42:43], v[0:1] op_sel_hi:[1,0]
	s_waitcnt vmcnt(1)
	v_pk_mul_f32 v[10:11], v[10:11], v[28:29]
	s_waitcnt vmcnt(0)
	v_lshlrev_b32_e32 v28, 16, v26
	v_and_b32_e32 v29, 0xffff0000, v26
	v_pk_mul_f32 v[12:13], v[12:13], v[30:31]
	v_lshlrev_b32_e32 v26, 16, v27
	v_and_b32_e32 v27, 0xffff0000, v27
	v_pk_mul_f32 v[10:11], v[10:11], v[28:29]
	v_pk_mul_f32 v[12:13], v[12:13], v[26:27]
	v_cvt_pk_bf16_f32 v10, v10, v11
	v_cvt_pk_bf16_f32 v11, v12, v13
	global_store_dwordx2 v[14:15], v[10:11], off offset:32
	global_load_dwordx4 v[10:13], v168, s[2:3] offset:96
	s_nop 0
	global_load_dwordx2 v[26:27], v[2:3], off offset:48
	v_pk_mul_f32 v[28:29], v[44:45], v[0:1] op_sel_hi:[1,0]
	v_pk_mul_f32 v[30:31], v[46:47], v[0:1] op_sel_hi:[1,0]
	s_waitcnt vmcnt(1)
	v_pk_mul_f32 v[10:11], v[10:11], v[28:29]
	s_waitcnt vmcnt(0)
	v_lshlrev_b32_e32 v28, 16, v26
	v_and_b32_e32 v29, 0xffff0000, v26
	v_pk_mul_f32 v[12:13], v[12:13], v[30:31]
	v_lshlrev_b32_e32 v26, 16, v27
	v_and_b32_e32 v27, 0xffff0000, v27
	v_pk_mul_f32 v[10:11], v[10:11], v[28:29]
	v_pk_mul_f32 v[12:13], v[12:13], v[26:27]
	v_cvt_pk_bf16_f32 v10, v10, v11
	v_cvt_pk_bf16_f32 v11, v12, v13
	global_store_dwordx2 v[14:15], v[10:11], off offset:48
	global_load_dwordx4 v[10:13], v168, s[2:3] offset:128
	s_nop 0
	global_load_dwordx2 v[26:27], v[2:3], off offset:64
	s_waitcnt vmcnt(1)
	v_pk_mul_f32 v[10:11], v[10:11], v[16:17]
	s_waitcnt vmcnt(0)
	v_lshlrev_b32_e32 v16, 16, v26
	v_and_b32_e32 v17, 0xffff0000, v26
	v_pk_mul_f32 v[12:13], v[12:13], v[18:19]
	v_lshlrev_b32_e32 v18, 16, v27
	v_and_b32_e32 v19, 0xffff0000, v27
	v_pk_mul_f32 v[10:11], v[10:11], v[16:17]
	v_pk_mul_f32 v[12:13], v[12:13], v[18:19]
	v_cvt_pk_bf16_f32 v10, v10, v11
	v_cvt_pk_bf16_f32 v11, v12, v13
	global_store_dwordx2 v[14:15], v[10:11], off offset:64
	global_load_dwordx4 v[10:13], v168, s[2:3] offset:160
	s_nop 0
	global_load_dwordx2 v[16:17], v[2:3], off offset:80
	v_pk_mul_f32 v[18:19], v[20:21], v[0:1] op_sel_hi:[1,0]
	v_pk_mul_f32 v[20:21], v[22:23], v[0:1] op_sel_hi:[1,0]
	s_waitcnt vmcnt(1)
	v_pk_mul_f32 v[10:11], v[10:11], v[18:19]
	s_waitcnt vmcnt(0)
	v_lshlrev_b32_e32 v18, 16, v16
	v_and_b32_e32 v19, 0xffff0000, v16
	v_pk_mul_f32 v[12:13], v[12:13], v[20:21]
	v_lshlrev_b32_e32 v16, 16, v17
	v_and_b32_e32 v17, 0xffff0000, v17
	v_pk_mul_f32 v[10:11], v[10:11], v[18:19]
	v_pk_mul_f32 v[12:13], v[12:13], v[16:17]
	v_cvt_pk_bf16_f32 v10, v10, v11
	v_cvt_pk_bf16_f32 v11, v12, v13
	global_store_dwordx2 v[14:15], v[10:11], off offset:80
	global_load_dwordx4 v[10:13], v168, s[2:3] offset:192
	s_nop 0
	global_load_dwordx2 v[16:17], v[2:3], off offset:96
	v_pk_mul_f32 v[18:19], v[24:25], v[0:1] op_sel_hi:[1,0]
	s_waitcnt vmcnt(1)
	v_pk_mul_f32 v[8:9], v[12:13], v[8:9]
	v_pk_mul_f32 v[10:11], v[10:11], v[18:19]
	s_waitcnt vmcnt(0)
	v_lshlrev_b32_e32 v18, 16, v16
	v_and_b32_e32 v19, 0xffff0000, v16
	v_lshlrev_b32_e32 v12, 16, v17
	v_and_b32_e32 v13, 0xffff0000, v17
	v_pk_mul_f32 v[10:11], v[10:11], v[18:19]
	v_pk_mul_f32 v[8:9], v[8:9], v[12:13]
	v_cvt_pk_bf16_f32 v10, v10, v11
	v_cvt_pk_bf16_f32 v11, v8, v9
	global_store_dwordx2 v[14:15], v[10:11], off offset:96
	global_load_dwordx4 v[8:11], v168, s[2:3] offset:224
	s_nop 0
	global_load_dwordx2 v[2:3], v[2:3], off offset:112
	s_waitcnt vmcnt(1)
	v_pk_mul_f32 v[6:7], v[8:9], v[6:7]
	s_waitcnt vmcnt(0)
	v_lshlrev_b32_e32 v8, 16, v2
	v_and_b32_e32 v9, 0xffff0000, v2
	v_pk_mul_f32 v[4:5], v[10:11], v[4:5]
	v_lshlrev_b32_e32 v2, 16, v3
	v_and_b32_e32 v3, 0xffff0000, v3
	v_pk_mul_f32 v[6:7], v[6:7], v[8:9]
	v_pk_mul_f32 v[2:3], v[4:5], v[2:3]
	v_cvt_pk_bf16_f32 v4, v6, v7
	v_cvt_pk_bf16_f32 v5, v2, v3
	global_store_dwordx2 v[14:15], v[4:5], off offset:112
